# GEMM: dropped the vmcnt(0) between a tile's epilogue stores and the next tile's K loop (counted waits in the loop only over-wait)
# baseline (speedup 1.0000x reference)
; template <class Epi, class Sched, bool ALIGN_EPI = false, bool SP2 = false>
; __device__ __forceinline__ void gemm_phase(PG8_LAS unsigned char* lds, const Gemm g, const Sched& S, const Epi& E) {
;     ...
;         const bool has_next = S.next(ui + 1, nxt);
;         const char* nA = has_next ? (const char*)g.A + (size_t)nxt.pm * tstep : cA; const char* nB = has_next ? (const char*)g.Bt + (size_t)nxt.pn * tstep : cB;
.LBB0_241:
	s_ashr_i32 s51, s50, 31
	s_lshl_b64 s[30:31], s[50:51], 19
	s_add_u32 s56, s96, s30
	s_addc_u32 s57, s97, s31
	s_and_b64 s[30:31], s[54:55], exec
	s_cselect_b32 s1, s57, s19
	s_cselect_b32 s30, s56, s18
	s_ashr_i32 s49, s48, 31
	s_lshl_b64 s[34:35], s[48:49], 19
	s_add_u32 s58, s25, s34
	s_addc_u32 s59, s26, s35
	s_and_b64 s[34:35], s[54:55], exec
	s_cselect_b32 s31, s59, s37
	s_cselect_b32 s34, s58, s36
	s_add_u32 s18, s18, 0x40080
	s_addc_u32 s19, s19, 0
	s_add_u32 s35, s36, 0x100

; template <class Epi, class Sched, bool ALIGN_EPI = false, bool SP2 = false>
; __device__ __forceinline__ void gemm_phase(PG8_LAS unsigned char* lds, const Gemm g, const Sched& S, const Epi& E) {
;     ...
;         for (int t = 0; t < nt; t += 2) {
	s_addc_u32 s49, s37, 0
	s_mov_b32 s51, -2


; #define PG8_STAGE(bufoff, gbase, voff) do { _Pragma("unroll") for (int _i = 0; _i < 2; ++_i) \
;         __builtin_amdgcn_global_load_lds((const unsigned*)((const char*)(gbase) + (voff)[_i]), (PG8_LAS unsigned*)(lds + (bufoff) + ldsw + _i * 8192), 16, 0, 0); } while (0)
; #define PG8_LDA(dst, b, h) do { _Pragma("unroll") for (int m = 0; m < 4; ++m) _Pragma("unroll") for (int k = 0; k < 2; ++k) dst[m][k] = *(const PG8_LAS bf16x8*)(lds + PG8_SA(b, h) + aoff + m * 2048 + k * 1024); } while (0)
; #define PG8_LDB(dst, b, h) do { _Pragma("unroll") for (int n = 0; n < 2; ++n) _Pragma("unroll") for (int k = 0; k < 2; ++k) dst[n][k] = *(const PG8_LAS bf16x8*)(lds + PG8_SB(b, h) + boff + n * 2048 + k * 1024); } while (0)
; #define PG8_MMA(ai, bj, At, Bt) do { __builtin_amdgcn_s_setprio(1); _Pragma("unroll") for (int m = 0; m < 4; ++m) _Pragma("unroll") for (int n = 0; n < 2; ++n) _Pragma("unroll") for (int k = 0; k < 2; ++k) \
;         acc[ai][bj][m][n] = __builtin_amdgcn_mfma_f32_16x16x32_bf16(Bt[n][k], At[m][k], acc[ai][bj][m][n], 0, 0, 0); __builtin_amdgcn_s_setprio(0); } while (0)
; #define PG8_WAIT_V(n) asm volatile("s_waitcnt vmcnt(" #n ")" ::: "memory")
; #define PG8_WAIT_L(n) asm volatile("s_waitcnt lgkmcnt(" #n ")" ::: "memory")
; #define PG8_BAR __builtin_amdgcn_s_barrier()
; #define PG8_SCHED __builtin_amdgcn_sched_barrier(0)
; template <class Epi, class Sched, bool ALIGN_EPI = false, bool SP2 = false>
; __device__ __forceinline__ void gemm_phase(PG8_LAS unsigned char* lds, const Gemm g, const Sched& S, const Epi& E) {
;     ...
;             const bool last = (t == nt - 2);
;             const char* a1 = cA + (size_t)(t + 1) * kstep;
;             const char* a2 = last ? nA : cA + (size_t)(t + 2) * kstep; const char* b2 = last ? nB : cB + (size_t)(t + 2) * kstep;
;             const char* a3 = a2 + kstep; const char* b3 = b2 + kstep;
;             if (last && has_next) S.a_ready(nxt);
;             if constexpr (SP2) {
;             PG8_LDB(B0, 0, 0); PG8_LDB(B1, 0, 1); PG8_SCHED; PG8_LDA(At, 0, 0); PG8_STAGE(PG8_SA(1, 1), a1 + hstep, voffA);
;             PG8_WAIT_V(8); PG8_WAIT_L(0); PG8_BAR; PG8_MMA(0, 0, At, B0); PG8_MMA(0, 1, At, B1); PG8_BAR; PG8_SCHED;
;             PG8_LDA(At, 0, 1); PG8_STAGE(PG8_SB(0, 0), b2, voffB); PG8_STAGE(PG8_SB(0, 1), b2 + hstep, voffB); PG8_STAGE(PG8_SA(0, 0), a2, voffA);
	s_add_u32 s36, s18, 0xfffc0080
	s_addc_u32 s37, s19, -1
	s_add_i32 s52, 0, 0x10000
	s_cmp_eq_u32 s51, 12
	s_cselect_b32 s63, s1, s37
	s_cselect_b32 s62, s30, s36
	s_cselect_b32 s37, s31, s49
	s_cselect_b32 s36, s34, s35
	s_add_i32 s67, 0, 0x14000
	v_add_u32_e32 v110, s52, v180
	v_add_u32_e32 v170, s67, v180
	ds_read_b128 v[98:101], v110
	ds_read_b128 v[102:105], v110 offset:1024
	ds_read_b128 v[106:109], v110 offset:2048
	ds_read_b128 v[110:113], v110 offset:3072
	ds_read_b128 v[158:161], v170
	ds_read_b128 v[162:165], v170 offset:1024
	ds_read_b128 v[166:169], v170 offset:2048
	ds_read_b128 v[170:173], v170 offset:3072
	v_lshl_add_u64 v[174:175], s[18:19], 0, v[154:155]
	s_add_i32 m0, s27, 0xc000
	ds_read_b128 v[184:187], v182
	ds_read_b128 v[194:197], v182 offset:1024
	ds_read_b128 v[198:201], v182 offset:2048
	ds_read_b128 v[202:205], v182 offset:3072
	ds_read_b128 v[206:209], v182 offset:4096
	ds_read_b128 v[210:213], v182 offset:5120
	ds_read_b128 v[214:217], v182 offset:6144
	ds_read_b128 v[218:221], v182 offset:7168
	global_load_lds_dwordx4 v[174:175], off
	v_lshl_add_u64 v[174:175], s[18:19], 0, v[156:157]
	s_add_i32 m0, s27, 0xe000
	s_nop 0
	global_load_lds_dwordx4 v[174:175], off
	s_waitcnt vmcnt(8)
	s_waitcnt lgkmcnt(0)
	s_barrier
	s_setprio 1
	s_waitcnt lgkmcnt(0)
	v_mfma_f32_16x16x32_bf16 v[142:145], v[98:101], v[184:187], 0
	v_mfma_f32_16x16x32_bf16 v[138:141], v[106:109], v[184:187], 0
	v_mfma_f32_16x16x32_bf16 v[126:129], v[98:101], v[198:201], 0
	v_mfma_f32_16x16x32_bf16 v[122:125], v[106:109], v[198:201], 0
	v_mfma_f32_16x16x32_bf16 v[94:97], v[98:101], v[206:209], 0
	v_mfma_f32_16x16x32_bf16 v[90:93], v[106:109], v[206:209], 0
	v_mfma_f32_16x16x32_bf16 v[78:81], v[98:101], v[214:217], 0
	v_mfma_f32_16x16x32_bf16 v[74:77], v[106:109], v[214:217], 0
	v_mfma_f32_16x16x32_bf16 v[142:145], v[102:105], v[194:197], v[142:145]
	v_mfma_f32_16x16x32_bf16 v[138:141], v[110:113], v[194:197], v[138:141]
	v_mfma_f32_16x16x32_bf16 v[126:129], v[102:105], v[202:205], v[126:129]
	v_mfma_f32_16x16x32_bf16 v[122:125], v[110:113], v[202:205], v[122:125]
	v_mfma_f32_16x16x32_bf16 v[94:97], v[102:105], v[210:213], v[94:97]
	v_mfma_f32_16x16x32_bf16 v[90:93], v[110:113], v[210:213], v[90:93]
	v_mfma_f32_16x16x32_bf16 v[78:81], v[102:105], v[218:221], v[78:81]
	v_mfma_f32_16x16x32_bf16 v[74:77], v[110:113], v[218:221], v[74:77]
	s_setprio 0
	s_setprio 1
	v_mfma_f32_16x16x32_bf16 v[134:137], v[158:161], v[184:187], 0
	v_mfma_f32_16x16x32_bf16 v[130:133], v[166:169], v[184:187], 0
	v_mfma_f32_16x16x32_bf16 v[118:121], v[158:161], v[198:201], 0
	v_mfma_f32_16x16x32_bf16 v[114:117], v[166:169], v[198:201], 0
	v_mfma_f32_16x16x32_bf16 v[86:89], v[158:161], v[206:209], 0
	v_mfma_f32_16x16x32_bf16 v[82:85], v[166:169], v[206:209], 0
	v_mfma_f32_16x16x32_bf16 v[70:73], v[158:161], v[214:217], 0
	v_mfma_f32_16x16x32_bf16 v[66:69], v[166:169], v[214:217], 0
	v_mfma_f32_16x16x32_bf16 v[134:137], v[162:165], v[194:197], v[134:137]
	v_mfma_f32_16x16x32_bf16 v[130:133], v[170:173], v[194:197], v[130:133]
	v_mfma_f32_16x16x32_bf16 v[118:121], v[162:165], v[202:205], v[118:121]
	v_mfma_f32_16x16x32_bf16 v[114:117], v[170:173], v[202:205], v[114:117]
	v_mfma_f32_16x16x32_bf16 v[86:89], v[162:165], v[210:213], v[86:89]
	v_mfma_f32_16x16x32_bf16 v[82:85], v[170:173], v[210:213], v[82:85]
	v_mfma_f32_16x16x32_bf16 v[70:73], v[162:165], v[218:221], v[70:73]
	v_mfma_f32_16x16x32_bf16 v[66:69], v[170:173], v[218:221], v[66:69]
	s_setprio 0
	s_barrier
	s_add_i32 s52, s52, s24
	v_lshl_add_u64 v[174:175], s[36:37], 0, v[0:1]
	s_mov_b32 m0, s52
	ds_read_b128 v[184:187], v182 offset:16384
	ds_read_b128 v[194:197], v182 offset:17408
	ds_read_b128 v[198:201], v182 offset:18432
	ds_read_b128 v[202:205], v182 offset:19456
	ds_read_b128 v[206:209], v182 offset:20480
	ds_read_b128 v[210:213], v182 offset:21504
	ds_read_b128 v[214:217], v182 offset:22528
	ds_read_b128 v[218:221], v182 offset:23552
	global_load_lds_dwordx4 v[174:175], off
	s_add_i32 m0, s52, 0x2000
	s_add_u32 s52, s36, 0x40000
	v_lshl_add_u64 v[178:179], s[36:37], 0, v[150:151]
	s_addc_u32 s53, s37, 0
	s_add_i32 s67, s67, s24
	global_load_lds_dwordx4 v[178:179], off
	v_lshl_add_u64 v[188:189], s[52:53], 0, v[0:1]
	s_mov_b32 m0, s67
	v_lshl_add_u64 v[222:223], s[62:63], 0, v[148:149]
	global_load_lds_dwordx4 v[188:189], off
	v_lshl_add_u64 v[188:189], s[52:53], 0, v[150:151]
	s_add_i32 m0, s67, 0x2000
	s_nop 0
	global_load_lds_dwordx4 v[188:189], off
	v_lshl_add_u64 v[188:189], s[62:63], 0, v[146:147]
	s_mov_b32 m0, s27
	s_nop 0
	global_load_lds_dwordx4 v[188:189], off
	s_mov_b32 m0, s28
	s_nop 0
	global_load_lds_dwordx4 v[222:223], off
	s_waitcnt vmcnt(8)
	s_waitcnt lgkmcnt(0)
	s_barrier
; #define PG8_STAGE(bufoff, gbase, voff) do { _Pragma("unroll") for (int _i = 0; _i < 2; ++_i) \
;         __builtin_amdgcn_global_load_lds((const unsigned*)((const char*)(gbase) + (voff)[_i]), (PG8_LAS unsigned*)(lds + (bufoff) + ldsw + _i * 8192), 16, 0, 0); } while (0)
; #define PG8_LDA(dst, b, h) do { _Pragma("unroll") for (int m = 0; m < 4; ++m) _Pragma("unroll") for (int k = 0; k < 2; ++k) dst[m][k] = *(const PG8_LAS bf16x8*)(lds + PG8_SA(b, h) + aoff + m * 2048 + k * 1024); } while (0)
; #define PG8_LDB(dst, b, h) do { _Pragma("unroll") for (int n = 0; n < 2; ++n) _Pragma("unroll") for (int k = 0; k < 2; ++k) dst[n][k] = *(const PG8_LAS bf16x8*)(lds + PG8_SB(b, h) + boff + n * 2048 + k * 1024); } while (0)
; #define PG8_MMA(ai, bj, At, Bt) do { __builtin_amdgcn_s_setprio(1); _Pragma("unroll") for (int m = 0; m < 4; ++m) _Pragma("unroll") for (int n = 0; n < 2; ++n) _Pragma("unroll") for (int k = 0; k < 2; ++k) \
;         acc[ai][bj][m][n] = __builtin_amdgcn_mfma_f32_16x16x32_bf16(Bt[n][k], At[m][k], acc[ai][bj][m][n], 0, 0, 0); __builtin_amdgcn_s_setprio(0); } while (0)
; #define PG8_WAIT_V(n) asm volatile("s_waitcnt vmcnt(" #n ")" ::: "memory")
; #define PG8_WAIT_L(n) asm volatile("s_waitcnt lgkmcnt(" #n ")" ::: "memory")
; #define PG8_BAR __builtin_amdgcn_s_barrier()
; #define PG8_SCHED __builtin_amdgcn_sched_barrier(0)
; template <class Epi, class Sched, bool ALIGN_EPI = false, bool SP2 = false>
; __device__ __forceinline__ void gemm_phase(PG8_LAS unsigned char* lds, const Gemm g, const Sched& S, const Epi& E) {
;     ...
;             PG8_WAIT_V(8); PG8_WAIT_L(0); PG8_BAR; PG8_MMA(1, 0, At, B0); PG8_MMA(1, 1, At, B1); PG8_BAR; PG8_SCHED;
;             PG8_LDB(B0, 1, 0); PG8_LDB(B1, 1, 1); PG8_SCHED; PG8_LDA(At, 1, 0); PG8_STAGE(PG8_SA(0, 1), a2 + hstep, voffA);
;             PG8_WAIT_V(8); PG8_WAIT_L(0); PG8_BAR; PG8_MMA(0, 0, At, B0); PG8_MMA(0, 1, At, B1); PG8_BAR; PG8_SCHED;
	s_setprio 1
	s_waitcnt lgkmcnt(0)
	v_mfma_f32_16x16x32_bf16 v[62:65], v[98:101], v[184:187], 0
	v_mfma_f32_16x16x32_bf16 v[58:61], v[106:109], v[184:187], 0
	v_mfma_f32_16x16x32_bf16 v[46:49], v[98:101], v[198:201], 0
	v_mfma_f32_16x16x32_bf16 v[42:45], v[106:109], v[198:201], 0
	v_mfma_f32_16x16x32_bf16 v[30:33], v[98:101], v[206:209], 0
	v_mfma_f32_16x16x32_bf16 v[26:29], v[106:109], v[206:209], 0
	v_mfma_f32_16x16x32_bf16 v[14:17], v[98:101], v[214:217], 0
	v_mfma_f32_16x16x32_bf16 v[10:13], v[106:109], v[214:217], 0
	v_mfma_f32_16x16x32_bf16 v[62:65], v[102:105], v[194:197], v[62:65]
	v_mfma_f32_16x16x32_bf16 v[58:61], v[110:113], v[194:197], v[58:61]
	v_mfma_f32_16x16x32_bf16 v[46:49], v[102:105], v[202:205], v[46:49]
	v_mfma_f32_16x16x32_bf16 v[42:45], v[110:113], v[202:205], v[42:45]
	v_mfma_f32_16x16x32_bf16 v[30:33], v[102:105], v[210:213], v[30:33]
	v_mfma_f32_16x16x32_bf16 v[26:29], v[110:113], v[210:213], v[26:29]
	v_mfma_f32_16x16x32_bf16 v[14:17], v[102:105], v[218:221], v[14:17]
	v_mfma_f32_16x16x32_bf16 v[10:13], v[110:113], v[218:221], v[10:13]
	s_setprio 0
	s_setprio 1
	v_mfma_f32_16x16x32_bf16 v[54:57], v[158:161], v[184:187], 0
	v_mfma_f32_16x16x32_bf16 v[50:53], v[166:169], v[184:187], 0
	v_mfma_f32_16x16x32_bf16 v[38:41], v[158:161], v[198:201], 0
	v_mfma_f32_16x16x32_bf16 v[34:37], v[166:169], v[198:201], 0
	v_mfma_f32_16x16x32_bf16 v[22:25], v[158:161], v[206:209], 0
	v_mfma_f32_16x16x32_bf16 v[18:21], v[166:169], v[206:209], 0
	v_mfma_f32_16x16x32_bf16 v[6:9], v[158:161], v[214:217], 0
	v_mfma_f32_16x16x32_bf16 v[2:5], v[166:169], v[214:217], 0
	v_mfma_f32_16x16x32_bf16 v[54:57], v[162:165], v[194:197], v[54:57]
	v_mfma_f32_16x16x32_bf16 v[50:53], v[170:173], v[194:197], v[50:53]
	v_mfma_f32_16x16x32_bf16 v[38:41], v[162:165], v[202:205], v[38:41]
	v_mfma_f32_16x16x32_bf16 v[34:37], v[170:173], v[202:205], v[34:37]
	v_mfma_f32_16x16x32_bf16 v[22:25], v[162:165], v[210:213], v[22:25]
	v_mfma_f32_16x16x32_bf16 v[18:21], v[170:173], v[210:213], v[18:21]
	v_mfma_f32_16x16x32_bf16 v[6:9], v[162:165], v[218:221], v[6:9]
	v_mfma_f32_16x16x32_bf16 v[2:5], v[170:173], v[218:221], v[2:5]
	s_setprio 0
	s_barrier
	s_add_i32 s67, 0, 0x18000
	s_add_i32 s68, 0, 0x1c000
	v_add_u32_e32 v110, s67, v180
	v_add_u32_e32 v170, s68, v180
	ds_read_b128 v[98:101], v110
	ds_read_b128 v[102:105], v110 offset:1024
	ds_read_b128 v[106:109], v110 offset:2048
	ds_read_b128 v[110:113], v110 offset:3072
	ds_read_b128 v[158:161], v170
	ds_read_b128 v[162:165], v170 offset:1024
	ds_read_b128 v[166:169], v170 offset:2048
	ds_read_b128 v[170:173], v170 offset:3072
	s_add_u32 s52, s62, 0x40000
	s_addc_u32 s53, s63, 0
	s_mov_b32 m0, s29
	v_lshl_add_u64 v[224:225], s[52:53], 0, v[146:147]
	ds_read_b128 v[184:187], v182 offset:32768
	ds_read_b128 v[194:197], v182 offset:33792
	ds_read_b128 v[198:201], v182 offset:34816
	ds_read_b128 v[202:205], v182 offset:35840
	ds_read_b128 v[206:209], v182 offset:36864
	ds_read_b128 v[210:213], v182 offset:37888
	ds_read_b128 v[214:217], v182 offset:38912
	ds_read_b128 v[218:221], v182 offset:39936
	global_load_lds_dwordx4 v[224:225], off
	v_lshl_add_u64 v[224:225], s[52:53], 0, v[148:149]
	s_mov_b32 m0, s61
	s_nop 0
	global_load_lds_dwordx4 v[224:225], off
	s_waitcnt vmcnt(8)
	s_waitcnt lgkmcnt(0)
	s_barrier
	s_setprio 1
	s_waitcnt lgkmcnt(0)
	v_mfma_f32_16x16x32_bf16 v[142:145], v[98:101], v[184:187], v[142:145]
	v_mfma_f32_16x16x32_bf16 v[138:141], v[106:109], v[184:187], v[138:141]
	v_mfma_f32_16x16x32_bf16 v[126:129], v[98:101], v[198:201], v[126:129]
	v_mfma_f32_16x16x32_bf16 v[122:125], v[106:109], v[198:201], v[122:125]
	v_mfma_f32_16x16x32_bf16 v[94:97], v[98:101], v[206:209], v[94:97]
	v_mfma_f32_16x16x32_bf16 v[90:93], v[106:109], v[206:209], v[90:93]
	v_mfma_f32_16x16x32_bf16 v[78:81], v[98:101], v[214:217], v[78:81]
	v_mfma_f32_16x16x32_bf16 v[74:77], v[106:109], v[214:217], v[74:77]
	v_mfma_f32_16x16x32_bf16 v[142:145], v[102:105], v[194:197], v[142:145]
	v_mfma_f32_16x16x32_bf16 v[138:141], v[110:113], v[194:197], v[138:141]
	v_mfma_f32_16x16x32_bf16 v[126:129], v[102:105], v[202:205], v[126:129]
	v_mfma_f32_16x16x32_bf16 v[122:125], v[110:113], v[202:205], v[122:125]
	v_mfma_f32_16x16x32_bf16 v[94:97], v[102:105], v[210:213], v[94:97]
	v_mfma_f32_16x16x32_bf16 v[90:93], v[110:113], v[210:213], v[90:93]
	v_mfma_f32_16x16x32_bf16 v[78:81], v[102:105], v[218:221], v[78:81]
	v_mfma_f32_16x16x32_bf16 v[74:77], v[110:113], v[218:221], v[74:77]
	s_setprio 0
	s_setprio 1
	v_mfma_f32_16x16x32_bf16 v[134:137], v[158:161], v[184:187], v[134:137]
	v_mfma_f32_16x16x32_bf16 v[130:133], v[166:169], v[184:187], v[130:133]
	v_mfma_f32_16x16x32_bf16 v[118:121], v[158:161], v[198:201], v[118:121]
	v_mfma_f32_16x16x32_bf16 v[114:117], v[166:169], v[198:201], v[114:117]
	v_mfma_f32_16x16x32_bf16 v[86:89], v[158:161], v[206:209], v[86:89]
	v_mfma_f32_16x16x32_bf16 v[82:85], v[166:169], v[206:209], v[82:85]
	v_mfma_f32_16x16x32_bf16 v[70:73], v[158:161], v[214:217], v[70:73]
	v_mfma_f32_16x16x32_bf16 v[66:69], v[166:169], v[214:217], v[66:69]
	v_mfma_f32_16x16x32_bf16 v[134:137], v[162:165], v[194:197], v[134:137]
	v_mfma_f32_16x16x32_bf16 v[130:133], v[170:173], v[194:197], v[130:133]
	v_mfma_f32_16x16x32_bf16 v[118:121], v[162:165], v[202:205], v[118:121]
	v_mfma_f32_16x16x32_bf16 v[114:117], v[170:173], v[202:205], v[114:117]
	v_mfma_f32_16x16x32_bf16 v[86:89], v[162:165], v[210:213], v[86:89]
	v_mfma_f32_16x16x32_bf16 v[82:85], v[170:173], v[210:213], v[82:85]
	v_mfma_f32_16x16x32_bf16 v[70:73], v[162:165], v[218:221], v[70:73]
	v_mfma_f32_16x16x32_bf16 v[66:69], v[170:173], v[218:221], v[66:69]
	s_setprio 0
	s_barrier
; #define PG8_STAGE(bufoff, gbase, voff) do { _Pragma("unroll") for (int _i = 0; _i < 2; ++_i) \
;         __builtin_amdgcn_global_load_lds((const unsigned*)((const char*)(gbase) + (voff)[_i]), (PG8_LAS unsigned*)(lds + (bufoff) + ldsw + _i * 8192), 16, 0, 0); } while (0)
; #define PG8_LDA(dst, b, h) do { _Pragma("unroll") for (int m = 0; m < 4; ++m) _Pragma("unroll") for (int k = 0; k < 2; ++k) dst[m][k] = *(const PG8_LAS bf16x8*)(lds + PG8_SA(b, h) + aoff + m * 2048 + k * 1024); } while (0)
; #define PG8_MMA(ai, bj, At, Bt) do { __builtin_amdgcn_s_setprio(1); _Pragma("unroll") for (int m = 0; m < 4; ++m) _Pragma("unroll") for (int n = 0; n < 2; ++n) _Pragma("unroll") for (int k = 0; k < 2; ++k) \
;         acc[ai][bj][m][n] = __builtin_amdgcn_mfma_f32_16x16x32_bf16(Bt[n][k], At[m][k], acc[ai][bj][m][n], 0, 0, 0); __builtin_amdgcn_s_setprio(0); } while (0)
; #define PG8_WAIT_V(n) asm volatile("s_waitcnt vmcnt(" #n ")" ::: "memory")
; #define PG8_WAIT_L(n) asm volatile("s_waitcnt lgkmcnt(" #n ")" ::: "memory")
; #define PG8_BAR __builtin_amdgcn_s_barrier()
; #define PG8_SCHED __builtin_amdgcn_sched_barrier(0)
; template <class Epi, class Sched, bool ALIGN_EPI = false, bool SP2 = false>
; __device__ __forceinline__ void gemm_phase(PG8_LAS unsigned char* lds, const Gemm g, const Sched& S, const Epi& E) {
;     ...
;         for (int t = 0; t < nt; t += 2) {
;     ...
;             PG8_LDA(At, 1, 1); PG8_STAGE(PG8_SB(1, 0), b3, voffB); PG8_STAGE(PG8_SB(1, 1), b3 + hstep, voffB); PG8_STAGE(PG8_SA(1, 0), a3, voffA);
;             PG8_WAIT_V(8); PG8_WAIT_L(0); PG8_BAR; PG8_MMA(1, 0, At, B0); PG8_MMA(1, 1, At, B1); PG8_BAR; PG8_SCHED;
	s_add_i32 s52, s67, s24
	v_lshl_add_u64 v[174:175], v[174:175], 0, s[8:9]
	s_mov_b32 m0, s52
	ds_read_b128 v[184:187], v182 offset:49152
	ds_read_b128 v[194:197], v182 offset:50176
	ds_read_b128 v[198:201], v182 offset:51200
	ds_read_b128 v[202:205], v182 offset:52224
	ds_read_b128 v[206:209], v182 offset:53248
	ds_read_b128 v[210:213], v182 offset:54272
	ds_read_b128 v[214:217], v182 offset:55296
	ds_read_b128 v[218:221], v182 offset:56320
	global_load_lds_dwordx4 v[174:175], off
	s_add_i32 m0, s52, 0x2000
	s_add_u32 s36, s36, 0x40080
	v_lshl_add_u64 v[174:175], v[178:179], 0, s[8:9]
	s_addc_u32 s37, s37, 0
	s_add_i32 s52, s68, s24
	global_load_lds_dwordx4 v[174:175], off
	v_lshl_add_u64 v[174:175], s[36:37], 0, v[0:1]
	s_mov_b32 m0, s52
	s_nop 0
	global_load_lds_dwordx4 v[174:175], off
	v_lshl_add_u64 v[174:175], s[36:37], 0, v[150:151]
	s_add_i32 m0, s52, 0x2000
	s_nop 0
	global_load_lds_dwordx4 v[174:175], off
	v_lshl_add_u64 v[174:175], v[188:189], 0, s[8:9]
	s_mov_b32 m0, s64
	s_nop 0
	global_load_lds_dwordx4 v[174:175], off
	v_lshl_add_u64 v[174:175], v[222:223], 0, s[8:9]
	s_mov_b32 m0, s65
	s_nop 0
	global_load_lds_dwordx4 v[174:175], off
	s_waitcnt vmcnt(8)
	s_waitcnt lgkmcnt(0)
	s_barrier
	s_setprio 1
	s_waitcnt lgkmcnt(0)
	v_mfma_f32_16x16x32_bf16 v[62:65], v[98:101], v[184:187], v[62:65]
	v_mfma_f32_16x16x32_bf16 v[58:61], v[106:109], v[184:187], v[58:61]
	v_mfma_f32_16x16x32_bf16 v[46:49], v[98:101], v[198:201], v[46:49]
	v_mfma_f32_16x16x32_bf16 v[42:45], v[106:109], v[198:201], v[42:45]
	v_mfma_f32_16x16x32_bf16 v[30:33], v[98:101], v[206:209], v[30:33]
	v_mfma_f32_16x16x32_bf16 v[26:29], v[106:109], v[206:209], v[26:29]
	v_mfma_f32_16x16x32_bf16 v[14:17], v[98:101], v[214:217], v[14:17]
	v_mfma_f32_16x16x32_bf16 v[10:13], v[106:109], v[214:217], v[10:13]
	v_mfma_f32_16x16x32_bf16 v[62:65], v[102:105], v[194:197], v[62:65]
	v_mfma_f32_16x16x32_bf16 v[58:61], v[110:113], v[194:197], v[58:61]
	v_mfma_f32_16x16x32_bf16 v[46:49], v[102:105], v[202:205], v[46:49]
	v_mfma_f32_16x16x32_bf16 v[42:45], v[110:113], v[202:205], v[42:45]
	v_mfma_f32_16x16x32_bf16 v[30:33], v[102:105], v[210:213], v[30:33]
	v_mfma_f32_16x16x32_bf16 v[26:29], v[110:113], v[210:213], v[26:29]
	v_mfma_f32_16x16x32_bf16 v[14:17], v[102:105], v[218:221], v[14:17]
	v_mfma_f32_16x16x32_bf16 v[10:13], v[110:113], v[218:221], v[10:13]
	s_setprio 0
	s_setprio 1
	v_mfma_f32_16x16x32_bf16 v[54:57], v[158:161], v[184:187], v[54:57]
	v_mfma_f32_16x16x32_bf16 v[50:53], v[166:169], v[184:187], v[50:53]
	v_mfma_f32_16x16x32_bf16 v[38:41], v[158:161], v[198:201], v[38:41]
	v_mfma_f32_16x16x32_bf16 v[34:37], v[166:169], v[198:201], v[34:37]
	v_mfma_f32_16x16x32_bf16 v[22:25], v[158:161], v[206:209], v[22:25]
	v_mfma_f32_16x16x32_bf16 v[18:21], v[166:169], v[206:209], v[18:21]
	v_mfma_f32_16x16x32_bf16 v[6:9], v[158:161], v[214:217], v[6:9]
	v_mfma_f32_16x16x32_bf16 v[2:5], v[166:169], v[214:217], v[2:5]
	v_mfma_f32_16x16x32_bf16 v[54:57], v[162:165], v[194:197], v[54:57]
	v_mfma_f32_16x16x32_bf16 v[50:53], v[170:173], v[194:197], v[50:53]
	v_mfma_f32_16x16x32_bf16 v[38:41], v[162:165], v[202:205], v[38:41]
	v_mfma_f32_16x16x32_bf16 v[34:37], v[170:173], v[202:205], v[34:37]
	v_mfma_f32_16x16x32_bf16 v[22:25], v[162:165], v[210:213], v[22:25]
	v_mfma_f32_16x16x32_bf16 v[18:21], v[170:173], v[210:213], v[18:21]
	v_mfma_f32_16x16x32_bf16 v[6:9], v[162:165], v[218:221], v[6:9]
	v_mfma_f32_16x16x32_bf16 v[2:5], v[170:173], v[218:221], v[2:5]
	s_setprio 0
	s_barrier
	s_add_i32 s51, s51, 2
	s_add_u32 s18, s18, 0x100
	s_addc_u32 s19, s19, 0
	s_add_u32 s35, s35, 0x100
	s_addc_u32 s49, s49, 0
	s_cmp_gt_u32 s51, 13

; template <class Epi, class Sched, bool ALIGN_EPI = false, bool SP2 = false>
; __device__ __forceinline__ void gemm_phase(PG8_LAS unsigned char* lds, const Gemm g, const Sched& S, const Epi& E) {
;     ...
;         const bool has_next = S.next(ui + 1, nxt);
;         const char* nA = has_next ? (const char*)g.A + (size_t)nxt.pm * tstep : cA; const char* nB = has_next ? (const char*)g.Bt + (size_t)nxt.pn * tstep : cB;
.LBB0_290:
	s_ashr_i32 s45, s44, 31
	s_lshl_b64 s[30:31], s[44:45], 19
	s_add_u32 s50, s25, s30
	s_addc_u32 s51, s26, s31
	s_and_b64 s[30:31], s[48:49], exec
	s_cselect_b32 s30, s51, s19
	s_cselect_b32 s31, s50, s18
	s_ashr_i32 s43, s42, 31
	s_lshl_b64 s[34:35], s[42:43], 19
	s_add_u32 s54, s96, s34
	s_addc_u32 s55, s97, s35
	s_and_b64 s[34:35], s[48:49], exec
	s_cselect_b32 s34, s55, s59
	s_cselect_b32 s35, s54, s58
	s_add_u32 s18, s18, 0x40080
	s_addc_u32 s19, s19, 0
	s_add_u32 s43, s58, 0x100

; template <class Epi, class Sched, bool ALIGN_EPI = false, bool SP2 = false>
; __device__ __forceinline__ void gemm_phase(PG8_LAS unsigned char* lds, const Gemm g, const Sched& S, const Epi& E) {
;     ...
;         for (int t = 0; t < nt; t += 2) {
	s_addc_u32 s45, s59, 0
	s_mov_b32 s52, -2


; #define PG8_STAGE(bufoff, gbase, voff) do { _Pragma("unroll") for (int _i = 0; _i < 2; ++_i) \
;         __builtin_amdgcn_global_load_lds((const unsigned*)((const char*)(gbase) + (voff)[_i]), (PG8_LAS unsigned*)(lds + (bufoff) + ldsw + _i * 8192), 16, 0, 0); } while (0)
; #define PG8_LDA(dst, b, h) do { _Pragma("unroll") for (int m = 0; m < 4; ++m) _Pragma("unroll") for (int k = 0; k < 2; ++k) dst[m][k] = *(const PG8_LAS bf16x8*)(lds + PG8_SA(b, h) + aoff + m * 2048 + k * 1024); } while (0)
; #define PG8_LDB(dst, b, h) do { _Pragma("unroll") for (int n = 0; n < 2; ++n) _Pragma("unroll") for (int k = 0; k < 2; ++k) dst[n][k] = *(const PG8_LAS bf16x8*)(lds + PG8_SB(b, h) + boff + n * 2048 + k * 1024); } while (0)
; #define PG8_MMA(ai, bj, At, Bt) do { __builtin_amdgcn_s_setprio(1); _Pragma("unroll") for (int m = 0; m < 4; ++m) _Pragma("unroll") for (int n = 0; n < 2; ++n) _Pragma("unroll") for (int k = 0; k < 2; ++k) \
;         acc[ai][bj][m][n] = __builtin_amdgcn_mfma_f32_16x16x32_bf16(Bt[n][k], At[m][k], acc[ai][bj][m][n], 0, 0, 0); __builtin_amdgcn_s_setprio(0); } while (0)
; #define PG8_WAIT_V(n) asm volatile("s_waitcnt vmcnt(" #n ")" ::: "memory")
; #define PG8_WAIT_L(n) asm volatile("s_waitcnt lgkmcnt(" #n ")" ::: "memory")
; #define PG8_BAR __builtin_amdgcn_s_barrier()
; #define PG8_SCHED __builtin_amdgcn_sched_barrier(0)
; template <class Epi, class Sched, bool ALIGN_EPI = false, bool SP2 = false>
; __device__ __forceinline__ void gemm_phase(PG8_LAS unsigned char* lds, const Gemm g, const Sched& S, const Epi& E) {
;     ...
;             const bool last = (t == nt - 2);
;             const char* a1 = cA + (size_t)(t + 1) * kstep;
;             const char* a2 = last ? nA : cA + (size_t)(t + 2) * kstep; const char* b2 = last ? nB : cB + (size_t)(t + 2) * kstep;
;             const char* a3 = a2 + kstep; const char* b3 = b2 + kstep;
;             if (last && has_next) S.a_ready(nxt);
;             if constexpr (SP2) {
;             PG8_LDB(B0, 0, 0); PG8_LDB(B1, 0, 1); PG8_SCHED; PG8_LDA(At, 0, 0); PG8_STAGE(PG8_SA(1, 1), a1 + hstep, voffA);
;             PG8_WAIT_V(8); PG8_WAIT_L(0); PG8_BAR; PG8_MMA(0, 0, At, B0); PG8_MMA(0, 1, At, B1); PG8_BAR; PG8_SCHED;
;             PG8_LDA(At, 0, 1); PG8_STAGE(PG8_SB(0, 0), b2, voffB); PG8_STAGE(PG8_SB(0, 1), b2 + hstep, voffB); PG8_STAGE(PG8_SA(0, 0), a2, voffA);
	s_add_u32 s53, s18, 0xfffc0080
	s_addc_u32 s58, s19, -1
	s_add_i32 s64, 0, 0x10000
	s_cmp_eq_u32 s52, 12
	s_cselect_b32 s61, s30, s58
	s_cselect_b32 s60, s31, s53
	s_cselect_b32 s59, s34, s45
	s_cselect_b32 s58, s35, s43
	s_add_i32 s53, 0, 0x14000
	v_add_u32_e32 v142, s64, v167
	v_add_u32_e32 v164, s53, v167
	ds_read_b128 v[130:133], v142
	ds_read_b128 v[134:137], v142 offset:1024
	ds_read_b128 v[138:141], v142 offset:2048
	ds_read_b128 v[142:145], v142 offset:3072
	ds_read_b128 v[156:159], v164
	ds_read_b128 v[160:163], v164 offset:1024
	ds_read_b128 v[170:173], v164 offset:2048
	ds_read_b128 v[174:177], v164 offset:3072
	v_lshl_add_u64 v[164:165], s[18:19], 0, v[152:153]
	s_add_i32 m0, s27, 0xc000
	ds_read_b128 v[178:181], v169
	ds_read_b128 v[182:185], v169 offset:1024
	ds_read_b128 v[186:189], v169 offset:2048
	ds_read_b128 v[194:197], v169 offset:3072
	ds_read_b128 v[198:201], v169 offset:4096
	ds_read_b128 v[202:205], v169 offset:5120
	ds_read_b128 v[206:209], v169 offset:6144
	ds_read_b128 v[210:213], v169 offset:7168
	global_load_lds_dwordx4 v[164:165], off
	v_lshl_add_u64 v[164:165], s[18:19], 0, v[154:155]
	s_add_i32 m0, s27, 0xe000
	s_nop 0
	global_load_lds_dwordx4 v[164:165], off
	s_waitcnt vmcnt(8)
	s_waitcnt lgkmcnt(0)
	s_barrier
	s_setprio 1
	s_waitcnt lgkmcnt(0)
	v_mfma_f32_16x16x32_bf16 v[126:129], v[130:133], v[178:181], 0
	v_mfma_f32_16x16x32_bf16 v[122:125], v[138:141], v[178:181], 0
	v_mfma_f32_16x16x32_bf16 v[114:117], v[130:133], v[186:189], 0
	v_mfma_f32_16x16x32_bf16 v[110:113], v[138:141], v[186:189], 0
	v_mfma_f32_16x16x32_bf16 v[102:105], v[130:133], v[198:201], 0
	v_mfma_f32_16x16x32_bf16 v[94:97], v[138:141], v[198:201], 0
	v_mfma_f32_16x16x32_bf16 v[86:89], v[130:133], v[206:209], 0
	v_mfma_f32_16x16x32_bf16 v[78:81], v[138:141], v[206:209], 0
	v_mfma_f32_16x16x32_bf16 v[126:129], v[134:137], v[182:185], v[126:129]
	v_mfma_f32_16x16x32_bf16 v[122:125], v[142:145], v[182:185], v[122:125]
	v_mfma_f32_16x16x32_bf16 v[114:117], v[134:137], v[194:197], v[114:117]
	v_mfma_f32_16x16x32_bf16 v[110:113], v[142:145], v[194:197], v[110:113]
	v_mfma_f32_16x16x32_bf16 v[102:105], v[134:137], v[202:205], v[102:105]
	v_mfma_f32_16x16x32_bf16 v[94:97], v[142:145], v[202:205], v[94:97]
	v_mfma_f32_16x16x32_bf16 v[86:89], v[134:137], v[210:213], v[86:89]
	v_mfma_f32_16x16x32_bf16 v[78:81], v[142:145], v[210:213], v[78:81]
	s_setprio 0
	s_setprio 1
	v_mfma_f32_16x16x32_bf16 v[118:121], v[156:159], v[178:181], 0
	v_mfma_f32_16x16x32_bf16 v[106:109], v[170:173], v[178:181], 0
	v_mfma_f32_16x16x32_bf16 v[98:101], v[156:159], v[186:189], 0
	v_mfma_f32_16x16x32_bf16 v[90:93], v[170:173], v[186:189], 0
	v_mfma_f32_16x16x32_bf16 v[82:85], v[156:159], v[198:201], 0
	v_mfma_f32_16x16x32_bf16 v[74:77], v[170:173], v[198:201], 0
	v_mfma_f32_16x16x32_bf16 v[70:73], v[156:159], v[206:209], 0
	v_mfma_f32_16x16x32_bf16 v[66:69], v[170:173], v[206:209], 0
	v_mfma_f32_16x16x32_bf16 v[118:121], v[160:163], v[182:185], v[118:121]
	v_mfma_f32_16x16x32_bf16 v[106:109], v[174:177], v[182:185], v[106:109]
	v_mfma_f32_16x16x32_bf16 v[98:101], v[160:163], v[194:197], v[98:101]
	v_mfma_f32_16x16x32_bf16 v[90:93], v[174:177], v[194:197], v[90:93]
	v_mfma_f32_16x16x32_bf16 v[82:85], v[160:163], v[202:205], v[82:85]
	v_mfma_f32_16x16x32_bf16 v[74:77], v[174:177], v[202:205], v[74:77]
	v_mfma_f32_16x16x32_bf16 v[70:73], v[160:163], v[210:213], v[70:73]
	v_mfma_f32_16x16x32_bf16 v[66:69], v[174:177], v[210:213], v[66:69]
	s_setprio 0
	s_barrier
	s_add_i32 s64, s64, s24
	v_lshl_add_u64 v[164:165], s[58:59], 0, v[0:1]
	s_mov_b32 m0, s64
	ds_read_b128 v[178:181], v169 offset:16384
	ds_read_b128 v[182:185], v169 offset:17408
	ds_read_b128 v[186:189], v169 offset:18432
	ds_read_b128 v[194:197], v169 offset:19456
	ds_read_b128 v[198:201], v169 offset:20480
	ds_read_b128 v[202:205], v169 offset:21504
	ds_read_b128 v[206:209], v169 offset:22528
	ds_read_b128 v[210:213], v169 offset:23552
	global_load_lds_dwordx4 v[164:165], off
	s_add_i32 m0, s64, 0x2000
	s_add_u32 s64, s58, 0x40000
	v_lshl_add_u64 v[214:215], s[58:59], 0, v[150:151]
	s_addc_u32 s65, s59, 0
	s_add_i32 s53, s53, s24
	global_load_lds_dwordx4 v[214:215], off
	v_lshl_add_u64 v[216:217], s[64:65], 0, v[0:1]
	s_mov_b32 m0, s53
	v_lshl_add_u64 v[218:219], s[60:61], 0, v[148:149]
	global_load_lds_dwordx4 v[216:217], off
	v_lshl_add_u64 v[216:217], s[64:65], 0, v[150:151]
	s_add_i32 m0, s53, 0x2000
	s_nop 0
	global_load_lds_dwordx4 v[216:217], off
	v_lshl_add_u64 v[216:217], s[60:61], 0, v[146:147]
	s_mov_b32 m0, s27
	s_nop 0
	global_load_lds_dwordx4 v[216:217], off
	s_mov_b32 m0, s28
	s_nop 0
	global_load_lds_dwordx4 v[218:219], off
	s_waitcnt vmcnt(8)
	s_waitcnt lgkmcnt(0)
	s_barrier
; #define PG8_STAGE(bufoff, gbase, voff) do { _Pragma("unroll") for (int _i = 0; _i < 2; ++_i) \
;         __builtin_amdgcn_global_load_lds((const unsigned*)((const char*)(gbase) + (voff)[_i]), (PG8_LAS unsigned*)(lds + (bufoff) + ldsw + _i * 8192), 16, 0, 0); } while (0)
; #define PG8_LDA(dst, b, h) do { _Pragma("unroll") for (int m = 0; m < 4; ++m) _Pragma("unroll") for (int k = 0; k < 2; ++k) dst[m][k] = *(const PG8_LAS bf16x8*)(lds + PG8_SA(b, h) + aoff + m * 2048 + k * 1024); } while (0)
; #define PG8_LDB(dst, b, h) do { _Pragma("unroll") for (int n = 0; n < 2; ++n) _Pragma("unroll") for (int k = 0; k < 2; ++k) dst[n][k] = *(const PG8_LAS bf16x8*)(lds + PG8_SB(b, h) + boff + n * 2048 + k * 1024); } while (0)
; #define PG8_MMA(ai, bj, At, Bt) do { __builtin_amdgcn_s_setprio(1); _Pragma("unroll") for (int m = 0; m < 4; ++m) _Pragma("unroll") for (int n = 0; n < 2; ++n) _Pragma("unroll") for (int k = 0; k < 2; ++k) \
;         acc[ai][bj][m][n] = __builtin_amdgcn_mfma_f32_16x16x32_bf16(Bt[n][k], At[m][k], acc[ai][bj][m][n], 0, 0, 0); __builtin_amdgcn_s_setprio(0); } while (0)
; #define PG8_WAIT_V(n) asm volatile("s_waitcnt vmcnt(" #n ")" ::: "memory")
; #define PG8_WAIT_L(n) asm volatile("s_waitcnt lgkmcnt(" #n ")" ::: "memory")
; #define PG8_BAR __builtin_amdgcn_s_barrier()
; #define PG8_SCHED __builtin_amdgcn_sched_barrier(0)
; template <class Epi, class Sched, bool ALIGN_EPI = false, bool SP2 = false>
; __device__ __forceinline__ void gemm_phase(PG8_LAS unsigned char* lds, const Gemm g, const Sched& S, const Epi& E) {
;     ...
;             PG8_WAIT_V(8); PG8_WAIT_L(0); PG8_BAR; PG8_MMA(1, 0, At, B0); PG8_MMA(1, 1, At, B1); PG8_BAR; PG8_SCHED;
;             PG8_LDB(B0, 1, 0); PG8_LDB(B1, 1, 1); PG8_SCHED; PG8_LDA(At, 1, 0); PG8_STAGE(PG8_SA(0, 1), a2 + hstep, voffA);
;             PG8_WAIT_V(8); PG8_WAIT_L(0); PG8_BAR; PG8_MMA(0, 0, At, B0); PG8_MMA(0, 1, At, B1); PG8_BAR; PG8_SCHED;
	s_setprio 1
	s_waitcnt lgkmcnt(0)
	v_mfma_f32_16x16x32_bf16 v[62:65], v[130:133], v[178:181], 0
	v_mfma_f32_16x16x32_bf16 v[58:61], v[138:141], v[178:181], 0
	v_mfma_f32_16x16x32_bf16 v[54:57], v[130:133], v[186:189], 0
	v_mfma_f32_16x16x32_bf16 v[46:49], v[138:141], v[186:189], 0
	v_mfma_f32_16x16x32_bf16 v[38:41], v[130:133], v[198:201], 0
	v_mfma_f32_16x16x32_bf16 v[30:33], v[138:141], v[198:201], 0
	v_mfma_f32_16x16x32_bf16 v[22:25], v[130:133], v[206:209], 0
	v_mfma_f32_16x16x32_bf16 v[14:17], v[138:141], v[206:209], 0
	v_mfma_f32_16x16x32_bf16 v[62:65], v[134:137], v[182:185], v[62:65]
	v_mfma_f32_16x16x32_bf16 v[58:61], v[142:145], v[182:185], v[58:61]
	v_mfma_f32_16x16x32_bf16 v[54:57], v[134:137], v[194:197], v[54:57]
	v_mfma_f32_16x16x32_bf16 v[46:49], v[142:145], v[194:197], v[46:49]
	v_mfma_f32_16x16x32_bf16 v[38:41], v[134:137], v[202:205], v[38:41]
	v_mfma_f32_16x16x32_bf16 v[30:33], v[142:145], v[202:205], v[30:33]
	v_mfma_f32_16x16x32_bf16 v[22:25], v[134:137], v[210:213], v[22:25]
	v_mfma_f32_16x16x32_bf16 v[14:17], v[142:145], v[210:213], v[14:17]
	s_setprio 0
	s_setprio 1
	v_mfma_f32_16x16x32_bf16 v[50:53], v[156:159], v[178:181], 0
	v_mfma_f32_16x16x32_bf16 v[42:45], v[170:173], v[178:181], 0
	v_mfma_f32_16x16x32_bf16 v[34:37], v[156:159], v[186:189], 0
	v_mfma_f32_16x16x32_bf16 v[26:29], v[170:173], v[186:189], 0
	v_mfma_f32_16x16x32_bf16 v[18:21], v[156:159], v[198:201], 0
	v_mfma_f32_16x16x32_bf16 v[10:13], v[170:173], v[198:201], 0
	v_mfma_f32_16x16x32_bf16 v[6:9], v[156:159], v[206:209], 0
	v_mfma_f32_16x16x32_bf16 v[2:5], v[170:173], v[206:209], 0
	v_mfma_f32_16x16x32_bf16 v[50:53], v[160:163], v[182:185], v[50:53]
	v_mfma_f32_16x16x32_bf16 v[42:45], v[174:177], v[182:185], v[42:45]
	v_mfma_f32_16x16x32_bf16 v[34:37], v[160:163], v[194:197], v[34:37]
	v_mfma_f32_16x16x32_bf16 v[26:29], v[174:177], v[194:197], v[26:29]
	v_mfma_f32_16x16x32_bf16 v[18:21], v[160:163], v[202:205], v[18:21]
	v_mfma_f32_16x16x32_bf16 v[10:13], v[174:177], v[202:205], v[10:13]
	v_mfma_f32_16x16x32_bf16 v[6:9], v[160:163], v[210:213], v[6:9]
	v_mfma_f32_16x16x32_bf16 v[2:5], v[174:177], v[210:213], v[2:5]
	s_setprio 0
	s_barrier
	s_add_i32 s53, 0, 0x18000
	s_add_i32 s64, 0, 0x1c000
	v_add_u32_e32 v142, s53, v167
	v_add_u32_e32 v174, s64, v167
	ds_read_b128 v[130:133], v142
	ds_read_b128 v[134:137], v142 offset:1024
	ds_read_b128 v[138:141], v142 offset:2048
	ds_read_b128 v[142:145], v142 offset:3072
	ds_read_b128 v[156:159], v174
	ds_read_b128 v[160:163], v174 offset:1024
	ds_read_b128 v[170:173], v174 offset:2048
	ds_read_b128 v[174:177], v174 offset:3072
	s_add_u32 s60, s60, 0x40000
	s_addc_u32 s61, s61, 0
	s_mov_b32 m0, s29
	v_lshl_add_u64 v[220:221], s[60:61], 0, v[146:147]
	ds_read_b128 v[178:181], v169 offset:32768
	ds_read_b128 v[182:185], v169 offset:33792
	ds_read_b128 v[186:189], v169 offset:34816
	ds_read_b128 v[194:197], v169 offset:35840
	ds_read_b128 v[198:201], v169 offset:36864
	ds_read_b128 v[202:205], v169 offset:37888
	ds_read_b128 v[206:209], v169 offset:38912
	ds_read_b128 v[210:213], v169 offset:39936
	global_load_lds_dwordx4 v[220:221], off
	v_lshl_add_u64 v[220:221], s[60:61], 0, v[148:149]
	s_mov_b32 m0, s47
	s_nop 0
	global_load_lds_dwordx4 v[220:221], off
	s_waitcnt vmcnt(8)
	s_waitcnt lgkmcnt(0)
	s_barrier
	s_setprio 1
	s_waitcnt lgkmcnt(0)
	v_mfma_f32_16x16x32_bf16 v[126:129], v[130:133], v[178:181], v[126:129]
	v_mfma_f32_16x16x32_bf16 v[122:125], v[138:141], v[178:181], v[122:125]
	v_mfma_f32_16x16x32_bf16 v[114:117], v[130:133], v[186:189], v[114:117]
	v_mfma_f32_16x16x32_bf16 v[110:113], v[138:141], v[186:189], v[110:113]
	v_mfma_f32_16x16x32_bf16 v[102:105], v[130:133], v[198:201], v[102:105]
	v_mfma_f32_16x16x32_bf16 v[94:97], v[138:141], v[198:201], v[94:97]
	v_mfma_f32_16x16x32_bf16 v[86:89], v[130:133], v[206:209], v[86:89]
	v_mfma_f32_16x16x32_bf16 v[78:81], v[138:141], v[206:209], v[78:81]
	v_mfma_f32_16x16x32_bf16 v[126:129], v[134:137], v[182:185], v[126:129]
	v_mfma_f32_16x16x32_bf16 v[122:125], v[142:145], v[182:185], v[122:125]
	v_mfma_f32_16x16x32_bf16 v[114:117], v[134:137], v[194:197], v[114:117]
	v_mfma_f32_16x16x32_bf16 v[110:113], v[142:145], v[194:197], v[110:113]
	v_mfma_f32_16x16x32_bf16 v[102:105], v[134:137], v[202:205], v[102:105]
	v_mfma_f32_16x16x32_bf16 v[94:97], v[142:145], v[202:205], v[94:97]
	v_mfma_f32_16x16x32_bf16 v[86:89], v[134:137], v[210:213], v[86:89]
	v_mfma_f32_16x16x32_bf16 v[78:81], v[142:145], v[210:213], v[78:81]
	s_setprio 0
	s_setprio 1
	v_mfma_f32_16x16x32_bf16 v[118:121], v[156:159], v[178:181], v[118:121]
	v_mfma_f32_16x16x32_bf16 v[106:109], v[170:173], v[178:181], v[106:109]
	v_mfma_f32_16x16x32_bf16 v[98:101], v[156:159], v[186:189], v[98:101]
	v_mfma_f32_16x16x32_bf16 v[90:93], v[170:173], v[186:189], v[90:93]
	v_mfma_f32_16x16x32_bf16 v[82:85], v[156:159], v[198:201], v[82:85]
	v_mfma_f32_16x16x32_bf16 v[74:77], v[170:173], v[198:201], v[74:77]
	v_mfma_f32_16x16x32_bf16 v[70:73], v[156:159], v[206:209], v[70:73]
	v_mfma_f32_16x16x32_bf16 v[66:69], v[170:173], v[206:209], v[66:69]
	v_mfma_f32_16x16x32_bf16 v[118:121], v[160:163], v[182:185], v[118:121]
	v_mfma_f32_16x16x32_bf16 v[106:109], v[174:177], v[182:185], v[106:109]
	v_mfma_f32_16x16x32_bf16 v[98:101], v[160:163], v[194:197], v[98:101]
	v_mfma_f32_16x16x32_bf16 v[90:93], v[174:177], v[194:197], v[90:93]
	v_mfma_f32_16x16x32_bf16 v[82:85], v[160:163], v[202:205], v[82:85]
	v_mfma_f32_16x16x32_bf16 v[74:77], v[174:177], v[202:205], v[74:77]
	v_mfma_f32_16x16x32_bf16 v[70:73], v[160:163], v[210:213], v[70:73]
	v_mfma_f32_16x16x32_bf16 v[66:69], v[174:177], v[210:213], v[66:69]
	s_setprio 0
	s_barrier
; #define PG8_STAGE(bufoff, gbase, voff) do { _Pragma("unroll") for (int _i = 0; _i < 2; ++_i) \
;         __builtin_amdgcn_global_load_lds((const unsigned*)((const char*)(gbase) + (voff)[_i]), (PG8_LAS unsigned*)(lds + (bufoff) + ldsw + _i * 8192), 16, 0, 0); } while (0)
; #define PG8_LDA(dst, b, h) do { _Pragma("unroll") for (int m = 0; m < 4; ++m) _Pragma("unroll") for (int k = 0; k < 2; ++k) dst[m][k] = *(const PG8_LAS bf16x8*)(lds + PG8_SA(b, h) + aoff + m * 2048 + k * 1024); } while (0)
; #define PG8_MMA(ai, bj, At, Bt) do { __builtin_amdgcn_s_setprio(1); _Pragma("unroll") for (int m = 0; m < 4; ++m) _Pragma("unroll") for (int n = 0; n < 2; ++n) _Pragma("unroll") for (int k = 0; k < 2; ++k) \
;         acc[ai][bj][m][n] = __builtin_amdgcn_mfma_f32_16x16x32_bf16(Bt[n][k], At[m][k], acc[ai][bj][m][n], 0, 0, 0); __builtin_amdgcn_s_setprio(0); } while (0)
; #define PG8_WAIT_V(n) asm volatile("s_waitcnt vmcnt(" #n ")" ::: "memory")
; #define PG8_WAIT_L(n) asm volatile("s_waitcnt lgkmcnt(" #n ")" ::: "memory")
; #define PG8_BAR __builtin_amdgcn_s_barrier()
; #define PG8_SCHED __builtin_amdgcn_sched_barrier(0)
; template <class Epi, class Sched, bool ALIGN_EPI = false, bool SP2 = false>
; __device__ __forceinline__ void gemm_phase(PG8_LAS unsigned char* lds, const Gemm g, const Sched& S, const Epi& E) {
;     ...
;             PG8_LDA(At, 1, 1); PG8_STAGE(PG8_SB(1, 0), b3, voffB); PG8_STAGE(PG8_SB(1, 1), b3 + hstep, voffB); PG8_STAGE(PG8_SA(1, 0), a3, voffA);
;             PG8_WAIT_V(8); PG8_WAIT_L(0); PG8_BAR; PG8_MMA(1, 0, At, B0); PG8_MMA(1, 1, At, B1); PG8_BAR; PG8_SCHED;
	s_add_i32 s53, s53, s24
	v_lshl_add_u64 v[164:165], v[164:165], 0, s[8:9]
	s_mov_b32 m0, s53
	ds_read_b128 v[178:181], v169 offset:49152
	ds_read_b128 v[182:185], v169 offset:50176
	ds_read_b128 v[186:189], v169 offset:51200
	ds_read_b128 v[194:197], v169 offset:52224
	ds_read_b128 v[198:201], v169 offset:53248
	ds_read_b128 v[202:205], v169 offset:54272
	ds_read_b128 v[206:209], v169 offset:55296
	ds_read_b128 v[210:213], v169 offset:56320
	global_load_lds_dwordx4 v[164:165], off
	s_add_i32 m0, s53, 0x2000
	s_add_u32 s58, s58, 0x40080
	v_lshl_add_u64 v[164:165], v[214:215], 0, s[8:9]
	s_addc_u32 s59, s59, 0
	s_add_i32 s53, s64, s24
	global_load_lds_dwordx4 v[164:165], off
	v_lshl_add_u64 v[164:165], s[58:59], 0, v[0:1]
	s_mov_b32 m0, s53
	s_nop 0
	global_load_lds_dwordx4 v[164:165], off
	v_lshl_add_u64 v[164:165], s[58:59], 0, v[150:151]
	s_add_i32 m0, s53, 0x2000
	s_nop 0
	global_load_lds_dwordx4 v[164:165], off
	v_lshl_add_u64 v[164:165], v[216:217], 0, s[8:9]
	s_mov_b32 m0, s57
	s_nop 0
	global_load_lds_dwordx4 v[164:165], off
	v_lshl_add_u64 v[164:165], v[218:219], 0, s[8:9]
	s_mov_b32 m0, s62
	s_nop 0
	global_load_lds_dwordx4 v[164:165], off
	s_waitcnt vmcnt(8)
	s_waitcnt lgkmcnt(0)
	s_barrier
	s_setprio 1
	s_waitcnt lgkmcnt(0)
	v_mfma_f32_16x16x32_bf16 v[62:65], v[130:133], v[178:181], v[62:65]
	v_mfma_f32_16x16x32_bf16 v[58:61], v[138:141], v[178:181], v[58:61]
	v_mfma_f32_16x16x32_bf16 v[54:57], v[130:133], v[186:189], v[54:57]
	v_mfma_f32_16x16x32_bf16 v[46:49], v[138:141], v[186:189], v[46:49]
	v_mfma_f32_16x16x32_bf16 v[38:41], v[130:133], v[198:201], v[38:41]
	v_mfma_f32_16x16x32_bf16 v[30:33], v[138:141], v[198:201], v[30:33]
	v_mfma_f32_16x16x32_bf16 v[22:25], v[130:133], v[206:209], v[22:25]
	v_mfma_f32_16x16x32_bf16 v[14:17], v[138:141], v[206:209], v[14:17]
	v_mfma_f32_16x16x32_bf16 v[62:65], v[134:137], v[182:185], v[62:65]
	v_mfma_f32_16x16x32_bf16 v[58:61], v[142:145], v[182:185], v[58:61]
	v_mfma_f32_16x16x32_bf16 v[54:57], v[134:137], v[194:197], v[54:57]
	v_mfma_f32_16x16x32_bf16 v[46:49], v[142:145], v[194:197], v[46:49]
	v_mfma_f32_16x16x32_bf16 v[38:41], v[134:137], v[202:205], v[38:41]
	v_mfma_f32_16x16x32_bf16 v[30:33], v[142:145], v[202:205], v[30:33]
	v_mfma_f32_16x16x32_bf16 v[22:25], v[134:137], v[210:213], v[22:25]
	v_mfma_f32_16x16x32_bf16 v[14:17], v[142:145], v[210:213], v[14:17]
	s_setprio 0
	s_setprio 1
	v_mfma_f32_16x16x32_bf16 v[50:53], v[156:159], v[178:181], v[50:53]
	v_mfma_f32_16x16x32_bf16 v[42:45], v[170:173], v[178:181], v[42:45]
	v_mfma_f32_16x16x32_bf16 v[34:37], v[156:159], v[186:189], v[34:37]
	v_mfma_f32_16x16x32_bf16 v[26:29], v[170:173], v[186:189], v[26:29]
	v_mfma_f32_16x16x32_bf16 v[18:21], v[156:159], v[198:201], v[18:21]
	v_mfma_f32_16x16x32_bf16 v[10:13], v[170:173], v[198:201], v[10:13]
	v_mfma_f32_16x16x32_bf16 v[6:9], v[156:159], v[206:209], v[6:9]
	v_mfma_f32_16x16x32_bf16 v[2:5], v[170:173], v[206:209], v[2:5]
	v_mfma_f32_16x16x32_bf16 v[50:53], v[160:163], v[182:185], v[50:53]
	v_mfma_f32_16x16x32_bf16 v[42:45], v[174:177], v[182:185], v[42:45]
	v_mfma_f32_16x16x32_bf16 v[34:37], v[160:163], v[194:197], v[34:37]
	v_mfma_f32_16x16x32_bf16 v[26:29], v[174:177], v[194:197], v[26:29]
	v_mfma_f32_16x16x32_bf16 v[18:21], v[160:163], v[202:205], v[18:21]
	v_mfma_f32_16x16x32_bf16 v[10:13], v[174:177], v[202:205], v[10:13]
	v_mfma_f32_16x16x32_bf16 v[6:9], v[160:163], v[210:213], v[6:9]
	v_mfma_f32_16x16x32_bf16 v[2:5], v[174:177], v[210:213], v[2:5]
	s_setprio 0
	s_barrier
	s_add_i32 s52, s52, 2
	s_add_u32 s18, s18, 0x100
	s_addc_u32 s19, s19, 0
	s_add_u32 s43, s43, 0x100
	s_addc_u32 s45, s45, 0
	s_cmp_gt_u32 s52, 13

; template <class Epi, class Sched, bool ALIGN_EPI = false, bool SP2 = false>
; __device__ __forceinline__ void gemm_phase(PG8_LAS unsigned char* lds, const Gemm g, const Sched& S, const Epi& E) {
;     ...
;         const bool has_next = S.next(ui + 1, nxt);
;         const char* nA = has_next ? (const char*)g.A + (size_t)nxt.pm * tstep : cA; const char* nB = has_next ? (const char*)g.Bt + (size_t)nxt.pn * tstep : cB;
;         for (int t = 0; t < nt; t += 2) {
.LBB0_452:
	s_ashr_i32 s51, s50, 31
	s_lshl_b64 s[30:31], s[50:51], 19
	s_add_u32 s56, s98, s30
	s_addc_u32 s57, s99, s31
	s_and_b64 s[30:31], s[54:55], exec
	s_cselect_b32 s30, s57, s19
	s_cselect_b32 s31, s56, s18
	s_ashr_i32 s49, s48, 31
	s_lshl_b64 s[34:35], s[48:49], 19
	s_add_u32 s58, s68, s34
	s_addc_u32 s59, s69, s35
	s_and_b64 s[34:35], s[54:55], exec
	s_cselect_b32 s34, s59, s65
	s_cselect_b32 s35, s58, s64
	s_add_u32 s18, s18, 0x40080
	s_addc_u32 s19, s19, 0
	s_add_u32 s49, s64, 0x100

; template <class Epi, class Sched, bool ALIGN_EPI = false, bool SP2 = false>
; __device__ __forceinline__ void gemm_phase(PG8_LAS unsigned char* lds, const Gemm g, const Sched& S, const Epi& E) {
;     ...
;         for (int t = 0; t < nt; t += 2) {
;             const bool last = (t == nt - 2);
;             const char* a1 = cA + (size_t)(t + 1) * kstep;
;             const char* a2 = last ? nA : cA + (size_t)(t + 2) * kstep; const char* b2 = last ? nB : cB + (size_t)(t + 2) * kstep;
	s_addc_u32 s51, s65, 0
	s_mov_b32 s52, -2


; #define PG8_STAGE(bufoff, gbase, voff) do { _Pragma("unroll") for (int _i = 0; _i < 2; ++_i) \
;         __builtin_amdgcn_global_load_lds((const unsigned*)((const char*)(gbase) + (voff)[_i]), (PG8_LAS unsigned*)(lds + (bufoff) + ldsw + _i * 8192), 16, 0, 0); } while (0)
; #define PG8_LDA(dst, b, h) do { _Pragma("unroll") for (int m = 0; m < 4; ++m) _Pragma("unroll") for (int k = 0; k < 2; ++k) dst[m][k] = *(const PG8_LAS bf16x8*)(lds + PG8_SA(b, h) + aoff + m * 2048 + k * 1024); } while (0)
; #define PG8_LDB(dst, b, h) do { _Pragma("unroll") for (int n = 0; n < 2; ++n) _Pragma("unroll") for (int k = 0; k < 2; ++k) dst[n][k] = *(const PG8_LAS bf16x8*)(lds + PG8_SB(b, h) + boff + n * 2048 + k * 1024); } while (0)
; #define PG8_MMA(ai, bj, At, Bt) do { __builtin_amdgcn_s_setprio(1); _Pragma("unroll") for (int m = 0; m < 4; ++m) _Pragma("unroll") for (int n = 0; n < 2; ++n) _Pragma("unroll") for (int k = 0; k < 2; ++k) \
;         acc[ai][bj][m][n] = __builtin_amdgcn_mfma_f32_16x16x32_bf16(Bt[n][k], At[m][k], acc[ai][bj][m][n], 0, 0, 0); __builtin_amdgcn_s_setprio(0); } while (0)
; #define PG8_WAIT_V(n) asm volatile("s_waitcnt vmcnt(" #n ")" ::: "memory")
; #define PG8_WAIT_L(n) asm volatile("s_waitcnt lgkmcnt(" #n ")" ::: "memory")
; #define PG8_BAR __builtin_amdgcn_s_barrier()
; #define PG8_SCHED __builtin_amdgcn_sched_barrier(0)
; template <class Epi, class Sched, bool ALIGN_EPI = false, bool SP2 = false>
; __device__ __forceinline__ void gemm_phase(PG8_LAS unsigned char* lds, const Gemm g, const Sched& S, const Epi& E) {
;     ...
;             const char* a2 = last ? nA : cA + (size_t)(t + 2) * kstep; const char* b2 = last ? nB : cB + (size_t)(t + 2) * kstep;
;             const char* a3 = a2 + kstep; const char* b3 = b2 + kstep;
;             if (last && has_next) S.a_ready(nxt);
;             if constexpr (SP2) {
;             PG8_LDB(B0, 0, 0); PG8_LDB(B1, 0, 1); PG8_SCHED; PG8_LDA(At, 0, 0); PG8_STAGE(PG8_SA(1, 1), a1 + hstep, voffA);
;             PG8_WAIT_V(8); PG8_WAIT_L(0); PG8_BAR; PG8_MMA(0, 0, At, B0); PG8_MMA(0, 1, At, B1); PG8_BAR; PG8_SCHED;
;             PG8_LDA(At, 0, 1); PG8_STAGE(PG8_SB(0, 0), b2, voffB); PG8_STAGE(PG8_SB(0, 1), b2 + hstep, voffB); PG8_STAGE(PG8_SA(0, 0), a2, voffA);
;             PG8_WAIT_V(8); PG8_WAIT_L(0); PG8_BAR; PG8_MMA(1, 0, At, B0); PG8_MMA(1, 1, At, B1); PG8_BAR; PG8_SCHED;
	s_add_u32 s53, s18, 0xfffc0080
	s_addc_u32 s64, s19, -1
	s_add_i32 s70, 0, 0x10000
	s_cmp_eq_u32 s52, 12
	s_cselect_b32 s67, s30, s64
	s_cselect_b32 s66, s31, s53
	s_cselect_b32 s65, s34, s51
	s_cselect_b32 s64, s35, s49
	s_add_i32 s53, 0, 0x14000
	v_add_u32_e32 v142, s70, v223
	v_add_u32_e32 v158, s53, v223
	ds_read_b128 v[130:133], v142
	ds_read_b128 v[134:137], v142 offset:1024
	ds_read_b128 v[138:141], v142 offset:2048
	ds_read_b128 v[142:145], v142 offset:3072
	ds_read_b128 v[146:149], v158
	ds_read_b128 v[150:153], v158 offset:1024
	ds_read_b128 v[154:157], v158 offset:2048
	ds_read_b128 v[158:161], v158 offset:3072
	v_lshl_add_u64 v[208:209], s[18:19], 0, v[200:201]
	s_add_i32 m0, s25, 0xc000
	ds_read_b128 v[162:165], v225
	ds_read_b128 v[166:169], v225 offset:1024
	ds_read_b128 v[170:173], v225 offset:2048
	ds_read_b128 v[174:177], v225 offset:3072
	ds_read_b128 v[178:181], v225 offset:4096
	ds_read_b128 v[182:185], v225 offset:5120
	ds_read_b128 v[186:189], v225 offset:6144
	ds_read_b128 v[204:207], v225 offset:7168
	global_load_lds_dwordx4 v[208:209], off
	v_lshl_add_u64 v[208:209], s[18:19], 0, v[202:203]
	s_add_i32 m0, s25, 0xe000
	s_nop 0
	global_load_lds_dwordx4 v[208:209], off
	s_waitcnt vmcnt(8)
	s_waitcnt lgkmcnt(0)
	s_barrier
	s_setprio 1
	s_waitcnt lgkmcnt(0)
	v_mfma_f32_16x16x32_bf16 v[126:129], v[130:133], v[162:165], 0
	v_mfma_f32_16x16x32_bf16 v[122:125], v[138:141], v[162:165], 0
	v_mfma_f32_16x16x32_bf16 v[110:113], v[130:133], v[170:173], 0
	v_mfma_f32_16x16x32_bf16 v[106:109], v[138:141], v[170:173], 0
	v_mfma_f32_16x16x32_bf16 v[98:101], v[130:133], v[178:181], 0
	v_mfma_f32_16x16x32_bf16 v[90:93], v[138:141], v[178:181], 0
	v_mfma_f32_16x16x32_bf16 v[82:85], v[130:133], v[186:189], 0
	v_mfma_f32_16x16x32_bf16 v[74:77], v[138:141], v[186:189], 0
	v_mfma_f32_16x16x32_bf16 v[126:129], v[134:137], v[166:169], v[126:129]
	v_mfma_f32_16x16x32_bf16 v[122:125], v[142:145], v[166:169], v[122:125]
	v_mfma_f32_16x16x32_bf16 v[110:113], v[134:137], v[174:177], v[110:113]
	v_mfma_f32_16x16x32_bf16 v[106:109], v[142:145], v[174:177], v[106:109]
	v_mfma_f32_16x16x32_bf16 v[98:101], v[134:137], v[182:185], v[98:101]
	v_mfma_f32_16x16x32_bf16 v[90:93], v[142:145], v[182:185], v[90:93]
	v_mfma_f32_16x16x32_bf16 v[82:85], v[134:137], v[204:207], v[82:85]
	v_mfma_f32_16x16x32_bf16 v[74:77], v[142:145], v[204:207], v[74:77]
	s_setprio 0
	s_setprio 1
	v_mfma_f32_16x16x32_bf16 v[118:121], v[146:149], v[162:165], 0
	v_mfma_f32_16x16x32_bf16 v[114:117], v[154:157], v[162:165], 0
	v_mfma_f32_16x16x32_bf16 v[102:105], v[146:149], v[170:173], 0
	v_mfma_f32_16x16x32_bf16 v[94:97], v[154:157], v[170:173], 0
	v_mfma_f32_16x16x32_bf16 v[86:89], v[146:149], v[178:181], 0
	v_mfma_f32_16x16x32_bf16 v[78:81], v[154:157], v[178:181], 0
	v_mfma_f32_16x16x32_bf16 v[70:73], v[146:149], v[186:189], 0
	v_mfma_f32_16x16x32_bf16 v[66:69], v[154:157], v[186:189], 0
	v_mfma_f32_16x16x32_bf16 v[118:121], v[150:153], v[166:169], v[118:121]
	v_mfma_f32_16x16x32_bf16 v[114:117], v[158:161], v[166:169], v[114:117]
	v_mfma_f32_16x16x32_bf16 v[102:105], v[150:153], v[174:177], v[102:105]
	v_mfma_f32_16x16x32_bf16 v[94:97], v[158:161], v[174:177], v[94:97]
	v_mfma_f32_16x16x32_bf16 v[86:89], v[150:153], v[182:185], v[86:89]
	v_mfma_f32_16x16x32_bf16 v[78:81], v[158:161], v[182:185], v[78:81]
	v_mfma_f32_16x16x32_bf16 v[70:73], v[150:153], v[204:207], v[70:73]
	v_mfma_f32_16x16x32_bf16 v[66:69], v[158:161], v[204:207], v[66:69]
	s_setprio 0
	s_barrier
	s_add_i32 s70, s70, s24
	v_lshl_add_u64 v[208:209], s[64:65], 0, v[0:1]
	s_mov_b32 m0, s70
	ds_read_b128 v[162:165], v225 offset:16384
	ds_read_b128 v[166:169], v225 offset:17408
	ds_read_b128 v[170:173], v225 offset:18432
	ds_read_b128 v[174:177], v225 offset:19456
	ds_read_b128 v[178:181], v225 offset:20480
	ds_read_b128 v[182:185], v225 offset:21504
	ds_read_b128 v[186:189], v225 offset:22528
	ds_read_b128 v[204:207], v225 offset:23552
	global_load_lds_dwordx4 v[208:209], off
	s_add_i32 m0, s70, 0x2000
	s_add_u32 s70, s64, 0x40000
	v_lshl_add_u64 v[210:211], s[64:65], 0, v[198:199]
	s_addc_u32 s71, s65, 0
	s_add_i32 s53, s53, s24
	global_load_lds_dwordx4 v[210:211], off
	v_lshl_add_u64 v[212:213], s[70:71], 0, v[0:1]
	s_mov_b32 m0, s53
	v_lshl_add_u64 v[214:215], s[66:67], 0, v[196:197]
	global_load_lds_dwordx4 v[212:213], off
	v_lshl_add_u64 v[212:213], s[70:71], 0, v[198:199]
	s_add_i32 m0, s53, 0x2000
	s_nop 0
	global_load_lds_dwordx4 v[212:213], off
	v_lshl_add_u64 v[212:213], s[66:67], 0, v[194:195]
	s_mov_b32 m0, s25
	s_nop 0
	global_load_lds_dwordx4 v[212:213], off
	s_mov_b32 m0, s26
	s_nop 0
	global_load_lds_dwordx4 v[214:215], off
	s_waitcnt vmcnt(8)
	s_waitcnt lgkmcnt(0)
	s_barrier
; #define PG8_STAGE(bufoff, gbase, voff) do { _Pragma("unroll") for (int _i = 0; _i < 2; ++_i) \
;         __builtin_amdgcn_global_load_lds((const unsigned*)((const char*)(gbase) + (voff)[_i]), (PG8_LAS unsigned*)(lds + (bufoff) + ldsw + _i * 8192), 16, 0, 0); } while (0)
; #define PG8_LDA(dst, b, h) do { _Pragma("unroll") for (int m = 0; m < 4; ++m) _Pragma("unroll") for (int k = 0; k < 2; ++k) dst[m][k] = *(const PG8_LAS bf16x8*)(lds + PG8_SA(b, h) + aoff + m * 2048 + k * 1024); } while (0)
; #define PG8_LDB(dst, b, h) do { _Pragma("unroll") for (int n = 0; n < 2; ++n) _Pragma("unroll") for (int k = 0; k < 2; ++k) dst[n][k] = *(const PG8_LAS bf16x8*)(lds + PG8_SB(b, h) + boff + n * 2048 + k * 1024); } while (0)
; #define PG8_MMA(ai, bj, At, Bt) do { __builtin_amdgcn_s_setprio(1); _Pragma("unroll") for (int m = 0; m < 4; ++m) _Pragma("unroll") for (int n = 0; n < 2; ++n) _Pragma("unroll") for (int k = 0; k < 2; ++k) \
;         acc[ai][bj][m][n] = __builtin_amdgcn_mfma_f32_16x16x32_bf16(Bt[n][k], At[m][k], acc[ai][bj][m][n], 0, 0, 0); __builtin_amdgcn_s_setprio(0); } while (0)
; #define PG8_WAIT_V(n) asm volatile("s_waitcnt vmcnt(" #n ")" ::: "memory")
; #define PG8_WAIT_L(n) asm volatile("s_waitcnt lgkmcnt(" #n ")" ::: "memory")
; #define PG8_BAR __builtin_amdgcn_s_barrier()
; #define PG8_SCHED __builtin_amdgcn_sched_barrier(0)
; template <class Epi, class Sched, bool ALIGN_EPI = false, bool SP2 = false>
; __device__ __forceinline__ void gemm_phase(PG8_LAS unsigned char* lds, const Gemm g, const Sched& S, const Epi& E) {
;     ...
;             PG8_WAIT_V(8); PG8_WAIT_L(0); PG8_BAR; PG8_MMA(1, 0, At, B0); PG8_MMA(1, 1, At, B1); PG8_BAR; PG8_SCHED;
;             PG8_LDB(B0, 1, 0); PG8_LDB(B1, 1, 1); PG8_SCHED; PG8_LDA(At, 1, 0); PG8_STAGE(PG8_SA(0, 1), a2 + hstep, voffA);
;             PG8_WAIT_V(8); PG8_WAIT_L(0); PG8_BAR; PG8_MMA(0, 0, At, B0); PG8_MMA(0, 1, At, B1); PG8_BAR; PG8_SCHED;
	s_setprio 1
	s_waitcnt lgkmcnt(0)
	v_mfma_f32_16x16x32_bf16 v[62:65], v[130:133], v[162:165], 0
	v_mfma_f32_16x16x32_bf16 v[58:61], v[138:141], v[162:165], 0
	v_mfma_f32_16x16x32_bf16 v[50:53], v[130:133], v[170:173], 0
	v_mfma_f32_16x16x32_bf16 v[42:45], v[138:141], v[170:173], 0
	v_mfma_f32_16x16x32_bf16 v[34:37], v[130:133], v[178:181], 0
	v_mfma_f32_16x16x32_bf16 v[26:29], v[138:141], v[178:181], 0
	v_mfma_f32_16x16x32_bf16 v[18:21], v[130:133], v[186:189], 0
	v_mfma_f32_16x16x32_bf16 v[10:13], v[138:141], v[186:189], 0
	v_mfma_f32_16x16x32_bf16 v[62:65], v[134:137], v[166:169], v[62:65]
	v_mfma_f32_16x16x32_bf16 v[58:61], v[142:145], v[166:169], v[58:61]
	v_mfma_f32_16x16x32_bf16 v[50:53], v[134:137], v[174:177], v[50:53]
	v_mfma_f32_16x16x32_bf16 v[42:45], v[142:145], v[174:177], v[42:45]
	v_mfma_f32_16x16x32_bf16 v[34:37], v[134:137], v[182:185], v[34:37]
	v_mfma_f32_16x16x32_bf16 v[26:29], v[142:145], v[182:185], v[26:29]
	v_mfma_f32_16x16x32_bf16 v[18:21], v[134:137], v[204:207], v[18:21]
	v_mfma_f32_16x16x32_bf16 v[10:13], v[142:145], v[204:207], v[10:13]
	s_setprio 0
	s_setprio 1
	v_mfma_f32_16x16x32_bf16 v[54:57], v[146:149], v[162:165], 0
	v_mfma_f32_16x16x32_bf16 v[46:49], v[154:157], v[162:165], 0
	v_mfma_f32_16x16x32_bf16 v[38:41], v[146:149], v[170:173], 0
	v_mfma_f32_16x16x32_bf16 v[30:33], v[154:157], v[170:173], 0
	v_mfma_f32_16x16x32_bf16 v[22:25], v[146:149], v[178:181], 0
	v_mfma_f32_16x16x32_bf16 v[14:17], v[154:157], v[178:181], 0
	v_mfma_f32_16x16x32_bf16 v[6:9], v[146:149], v[186:189], 0
	v_mfma_f32_16x16x32_bf16 v[2:5], v[154:157], v[186:189], 0
	v_mfma_f32_16x16x32_bf16 v[54:57], v[150:153], v[166:169], v[54:57]
	v_mfma_f32_16x16x32_bf16 v[46:49], v[158:161], v[166:169], v[46:49]
	v_mfma_f32_16x16x32_bf16 v[38:41], v[150:153], v[174:177], v[38:41]
	v_mfma_f32_16x16x32_bf16 v[30:33], v[158:161], v[174:177], v[30:33]
	v_mfma_f32_16x16x32_bf16 v[22:25], v[150:153], v[182:185], v[22:25]
	v_mfma_f32_16x16x32_bf16 v[14:17], v[158:161], v[182:185], v[14:17]
	v_mfma_f32_16x16x32_bf16 v[6:9], v[150:153], v[204:207], v[6:9]
	v_mfma_f32_16x16x32_bf16 v[2:5], v[158:161], v[204:207], v[2:5]
	s_setprio 0
	s_barrier
	s_add_i32 s53, 0, 0x18000
	s_add_i32 s70, 0, 0x1c000
	v_add_u32_e32 v142, s53, v223
	v_add_u32_e32 v158, s70, v223
	ds_read_b128 v[130:133], v142
	ds_read_b128 v[134:137], v142 offset:1024
	ds_read_b128 v[138:141], v142 offset:2048
	ds_read_b128 v[142:145], v142 offset:3072
	ds_read_b128 v[146:149], v158
	ds_read_b128 v[150:153], v158 offset:1024
	ds_read_b128 v[154:157], v158 offset:2048
	ds_read_b128 v[158:161], v158 offset:3072
	s_add_u32 s66, s66, 0x40000
	s_addc_u32 s67, s67, 0
	s_mov_b32 m0, s27
	v_lshl_add_u64 v[216:217], s[66:67], 0, v[194:195]
	ds_read_b128 v[162:165], v225 offset:32768
	ds_read_b128 v[166:169], v225 offset:33792
	ds_read_b128 v[170:173], v225 offset:34816
	ds_read_b128 v[174:177], v225 offset:35840
	ds_read_b128 v[178:181], v225 offset:36864
	ds_read_b128 v[182:185], v225 offset:37888
	ds_read_b128 v[186:189], v225 offset:38912
	ds_read_b128 v[204:207], v225 offset:39936
	global_load_lds_dwordx4 v[216:217], off
	v_lshl_add_u64 v[216:217], s[66:67], 0, v[196:197]
	s_mov_b32 m0, s28
	s_nop 0
	global_load_lds_dwordx4 v[216:217], off
	s_waitcnt vmcnt(8)
	s_waitcnt lgkmcnt(0)
	s_barrier
	s_setprio 1
	s_waitcnt lgkmcnt(0)
	v_mfma_f32_16x16x32_bf16 v[126:129], v[130:133], v[162:165], v[126:129]
	v_mfma_f32_16x16x32_bf16 v[122:125], v[138:141], v[162:165], v[122:125]
	v_mfma_f32_16x16x32_bf16 v[110:113], v[130:133], v[170:173], v[110:113]
	v_mfma_f32_16x16x32_bf16 v[106:109], v[138:141], v[170:173], v[106:109]
	v_mfma_f32_16x16x32_bf16 v[98:101], v[130:133], v[178:181], v[98:101]
	v_mfma_f32_16x16x32_bf16 v[90:93], v[138:141], v[178:181], v[90:93]
	v_mfma_f32_16x16x32_bf16 v[82:85], v[130:133], v[186:189], v[82:85]
	v_mfma_f32_16x16x32_bf16 v[74:77], v[138:141], v[186:189], v[74:77]
	v_mfma_f32_16x16x32_bf16 v[126:129], v[134:137], v[166:169], v[126:129]
	v_mfma_f32_16x16x32_bf16 v[122:125], v[142:145], v[166:169], v[122:125]
	v_mfma_f32_16x16x32_bf16 v[110:113], v[134:137], v[174:177], v[110:113]
	v_mfma_f32_16x16x32_bf16 v[106:109], v[142:145], v[174:177], v[106:109]
	v_mfma_f32_16x16x32_bf16 v[98:101], v[134:137], v[182:185], v[98:101]
	v_mfma_f32_16x16x32_bf16 v[90:93], v[142:145], v[182:185], v[90:93]
	v_mfma_f32_16x16x32_bf16 v[82:85], v[134:137], v[204:207], v[82:85]
	v_mfma_f32_16x16x32_bf16 v[74:77], v[142:145], v[204:207], v[74:77]
	s_setprio 0
	s_setprio 1
	v_mfma_f32_16x16x32_bf16 v[118:121], v[146:149], v[162:165], v[118:121]
	v_mfma_f32_16x16x32_bf16 v[114:117], v[154:157], v[162:165], v[114:117]
	v_mfma_f32_16x16x32_bf16 v[102:105], v[146:149], v[170:173], v[102:105]
	v_mfma_f32_16x16x32_bf16 v[94:97], v[154:157], v[170:173], v[94:97]
	v_mfma_f32_16x16x32_bf16 v[86:89], v[146:149], v[178:181], v[86:89]
	v_mfma_f32_16x16x32_bf16 v[78:81], v[154:157], v[178:181], v[78:81]
	v_mfma_f32_16x16x32_bf16 v[70:73], v[146:149], v[186:189], v[70:73]
	v_mfma_f32_16x16x32_bf16 v[66:69], v[154:157], v[186:189], v[66:69]
	v_mfma_f32_16x16x32_bf16 v[118:121], v[150:153], v[166:169], v[118:121]
	v_mfma_f32_16x16x32_bf16 v[114:117], v[158:161], v[166:169], v[114:117]
	v_mfma_f32_16x16x32_bf16 v[102:105], v[150:153], v[174:177], v[102:105]
	v_mfma_f32_16x16x32_bf16 v[94:97], v[158:161], v[174:177], v[94:97]
	v_mfma_f32_16x16x32_bf16 v[86:89], v[150:153], v[182:185], v[86:89]
	v_mfma_f32_16x16x32_bf16 v[78:81], v[158:161], v[182:185], v[78:81]
	v_mfma_f32_16x16x32_bf16 v[70:73], v[150:153], v[204:207], v[70:73]
	v_mfma_f32_16x16x32_bf16 v[66:69], v[158:161], v[204:207], v[66:69]
	s_setprio 0
	s_barrier
; #define PG8_STAGE(bufoff, gbase, voff) do { _Pragma("unroll") for (int _i = 0; _i < 2; ++_i) \
;         __builtin_amdgcn_global_load_lds((const unsigned*)((const char*)(gbase) + (voff)[_i]), (PG8_LAS unsigned*)(lds + (bufoff) + ldsw + _i * 8192), 16, 0, 0); } while (0)
; #define PG8_LDA(dst, b, h) do { _Pragma("unroll") for (int m = 0; m < 4; ++m) _Pragma("unroll") for (int k = 0; k < 2; ++k) dst[m][k] = *(const PG8_LAS bf16x8*)(lds + PG8_SA(b, h) + aoff + m * 2048 + k * 1024); } while (0)
; #define PG8_MMA(ai, bj, At, Bt) do { __builtin_amdgcn_s_setprio(1); _Pragma("unroll") for (int m = 0; m < 4; ++m) _Pragma("unroll") for (int n = 0; n < 2; ++n) _Pragma("unroll") for (int k = 0; k < 2; ++k) \
;         acc[ai][bj][m][n] = __builtin_amdgcn_mfma_f32_16x16x32_bf16(Bt[n][k], At[m][k], acc[ai][bj][m][n], 0, 0, 0); __builtin_amdgcn_s_setprio(0); } while (0)
; #define PG8_WAIT_V(n) asm volatile("s_waitcnt vmcnt(" #n ")" ::: "memory")
; #define PG8_WAIT_L(n) asm volatile("s_waitcnt lgkmcnt(" #n ")" ::: "memory")
; #define PG8_BAR __builtin_amdgcn_s_barrier()
; #define PG8_SCHED __builtin_amdgcn_sched_barrier(0)
; template <class Epi, class Sched, bool ALIGN_EPI = false, bool SP2 = false>
; __device__ __forceinline__ void gemm_phase(PG8_LAS unsigned char* lds, const Gemm g, const Sched& S, const Epi& E) {
;     ...
;             PG8_LDA(At, 1, 1); PG8_STAGE(PG8_SB(1, 0), b3, voffB); PG8_STAGE(PG8_SB(1, 1), b3 + hstep, voffB); PG8_STAGE(PG8_SA(1, 0), a3, voffA);
;             PG8_WAIT_V(8); PG8_WAIT_L(0); PG8_BAR; PG8_MMA(1, 0, At, B0); PG8_MMA(1, 1, At, B1); PG8_BAR; PG8_SCHED;
	s_add_i32 s53, s53, s24
	v_lshl_add_u64 v[208:209], v[208:209], 0, s[8:9]
	s_mov_b32 m0, s53
	ds_read_b128 v[162:165], v225 offset:49152
	ds_read_b128 v[166:169], v225 offset:50176
	ds_read_b128 v[170:173], v225 offset:51200
	ds_read_b128 v[174:177], v225 offset:52224
	ds_read_b128 v[178:181], v225 offset:53248
	ds_read_b128 v[182:185], v225 offset:54272
	ds_read_b128 v[186:189], v225 offset:55296
	ds_read_b128 v[204:207], v225 offset:56320
	global_load_lds_dwordx4 v[208:209], off
	s_add_i32 m0, s53, 0x2000
	s_add_u32 s64, s64, 0x40080
	v_lshl_add_u64 v[208:209], v[210:211], 0, s[8:9]
	s_addc_u32 s65, s65, 0
	s_add_i32 s53, s70, s24
	global_load_lds_dwordx4 v[208:209], off
	v_lshl_add_u64 v[208:209], s[64:65], 0, v[0:1]
	s_mov_b32 m0, s53
	s_nop 0
	global_load_lds_dwordx4 v[208:209], off
	v_lshl_add_u64 v[208:209], s[64:65], 0, v[198:199]
	s_add_i32 m0, s53, 0x2000
	s_nop 0
	global_load_lds_dwordx4 v[208:209], off
	v_lshl_add_u64 v[208:209], v[212:213], 0, s[8:9]
	s_mov_b32 m0, s29
	s_nop 0
	global_load_lds_dwordx4 v[208:209], off
	v_lshl_add_u64 v[208:209], v[214:215], 0, s[8:9]
	s_mov_b32 m0, s61
	s_nop 0
	global_load_lds_dwordx4 v[208:209], off
	s_waitcnt vmcnt(8)
	s_waitcnt lgkmcnt(0)
	s_barrier
	s_setprio 1
	s_waitcnt lgkmcnt(0)
	v_mfma_f32_16x16x32_bf16 v[62:65], v[130:133], v[162:165], v[62:65]
	v_mfma_f32_16x16x32_bf16 v[58:61], v[138:141], v[162:165], v[58:61]
	v_mfma_f32_16x16x32_bf16 v[50:53], v[130:133], v[170:173], v[50:53]
	v_mfma_f32_16x16x32_bf16 v[42:45], v[138:141], v[170:173], v[42:45]
	v_mfma_f32_16x16x32_bf16 v[34:37], v[130:133], v[178:181], v[34:37]
	v_mfma_f32_16x16x32_bf16 v[26:29], v[138:141], v[178:181], v[26:29]
	v_mfma_f32_16x16x32_bf16 v[18:21], v[130:133], v[186:189], v[18:21]
	v_mfma_f32_16x16x32_bf16 v[10:13], v[138:141], v[186:189], v[10:13]
	v_mfma_f32_16x16x32_bf16 v[62:65], v[134:137], v[166:169], v[62:65]
	v_mfma_f32_16x16x32_bf16 v[58:61], v[142:145], v[166:169], v[58:61]
	v_mfma_f32_16x16x32_bf16 v[50:53], v[134:137], v[174:177], v[50:53]
	v_mfma_f32_16x16x32_bf16 v[42:45], v[142:145], v[174:177], v[42:45]
	v_mfma_f32_16x16x32_bf16 v[34:37], v[134:137], v[182:185], v[34:37]
	v_mfma_f32_16x16x32_bf16 v[26:29], v[142:145], v[182:185], v[26:29]
	v_mfma_f32_16x16x32_bf16 v[18:21], v[134:137], v[204:207], v[18:21]
	v_mfma_f32_16x16x32_bf16 v[10:13], v[142:145], v[204:207], v[10:13]
	s_setprio 0
	s_setprio 1
	v_mfma_f32_16x16x32_bf16 v[54:57], v[146:149], v[162:165], v[54:57]
	v_mfma_f32_16x16x32_bf16 v[46:49], v[154:157], v[162:165], v[46:49]
	v_mfma_f32_16x16x32_bf16 v[38:41], v[146:149], v[170:173], v[38:41]
	v_mfma_f32_16x16x32_bf16 v[30:33], v[154:157], v[170:173], v[30:33]
	v_mfma_f32_16x16x32_bf16 v[22:25], v[146:149], v[178:181], v[22:25]
	v_mfma_f32_16x16x32_bf16 v[14:17], v[154:157], v[178:181], v[14:17]
	v_mfma_f32_16x16x32_bf16 v[6:9], v[146:149], v[186:189], v[6:9]
	v_mfma_f32_16x16x32_bf16 v[2:5], v[154:157], v[186:189], v[2:5]
	v_mfma_f32_16x16x32_bf16 v[54:57], v[150:153], v[166:169], v[54:57]
	v_mfma_f32_16x16x32_bf16 v[46:49], v[158:161], v[166:169], v[46:49]
	v_mfma_f32_16x16x32_bf16 v[38:41], v[150:153], v[174:177], v[38:41]
	v_mfma_f32_16x16x32_bf16 v[30:33], v[158:161], v[174:177], v[30:33]
	v_mfma_f32_16x16x32_bf16 v[22:25], v[150:153], v[182:185], v[22:25]
	v_mfma_f32_16x16x32_bf16 v[14:17], v[158:161], v[182:185], v[14:17]
	v_mfma_f32_16x16x32_bf16 v[6:9], v[150:153], v[204:207], v[6:9]
	v_mfma_f32_16x16x32_bf16 v[2:5], v[158:161], v[204:207], v[2:5]
	s_setprio 0
	s_barrier
	s_add_i32 s52, s52, 2
	s_add_u32 s18, s18, 0x100
	s_addc_u32 s19, s19, 0
	s_add_u32 s49, s49, 0x100
	s_addc_u32 s51, s51, 0
	s_cmp_gt_u32 s52, 13

; template <class Epi, class Sched, bool ALIGN_EPI = false, bool SP2 = false>
; __device__ __forceinline__ void gemm_phase(PG8_LAS unsigned char* lds, const Gemm g, const Sched& S, const Epi& E) {
;     ...
;         const bool has_next = S.next(ui + 1, nxt);
;         const char* nA = has_next ? (const char*)g.A + (size_t)nxt.pm * tstep : cA; const char* nB = has_next ? (const char*)g.Bt + (size_t)nxt.pn * tstep : cB;
;         for (int t = 0; t < nt; t += 2) {
.LBB0_486:
	s_ashr_i32 s47, s46, 31
	s_lshl_b64 s[30:31], s[46:47], 19
	s_add_u32 s50, s98, s30
	s_addc_u32 s51, s99, s31
	s_and_b64 s[30:31], s[48:49], exec
	s_cselect_b32 s30, s51, s19
	s_cselect_b32 s31, s50, s18
	s_ashr_i32 s45, s44, 31
	s_lshl_b64 s[34:35], s[44:45], 19
	s_add_u32 s54, s68, s34
	s_addc_u32 s55, s69, s35
	s_and_b64 s[34:35], s[48:49], exec
	s_cselect_b32 s34, s55, s61
	s_cselect_b32 s35, s54, s60
	s_add_u32 s18, s18, 0x40080
	s_addc_u32 s19, s19, 0
	s_add_u32 s45, s60, 0x100

; template <class Epi, class Sched, bool ALIGN_EPI = false, bool SP2 = false>
; __device__ __forceinline__ void gemm_phase(PG8_LAS unsigned char* lds, const Gemm g, const Sched& S, const Epi& E) {
;     ...
;         for (int t = 0; t < nt; t += 2) {
;             const bool last = (t == nt - 2);
;             const char* a1 = cA + (size_t)(t + 1) * kstep;
;             const char* a2 = last ? nA : cA + (size_t)(t + 2) * kstep; const char* b2 = last ? nB : cB + (size_t)(t + 2) * kstep;
	s_addc_u32 s47, s61, 0
	s_mov_b32 s52, -2


; template <class Epi, class Sched, bool ALIGN_EPI = false, bool SP2 = false>
; __device__ __forceinline__ void gemm_phase(PG8_LAS unsigned char* lds, const Gemm g, const Sched& S, const Epi& E) {
;     ...
;     for (;;) {
;         const bool has_next = S.next(ui + 1, nxt);
;         const char* nA = has_next ? (const char*)g.A + (size_t)nxt.pm * tstep : cA; const char* nB = has_next ? (const char*)g.Bt + (size_t)nxt.pn * tstep : cB;
;         for (int t = 0; t < nt; t += 2) {
	s_waitcnt lgkmcnt(0)


; #define PG8_STAGE(bufoff, gbase, voff) do { _Pragma("unroll") for (int _i = 0; _i < 2; ++_i) \
;         __builtin_amdgcn_global_load_lds((const unsigned*)((const char*)(gbase) + (voff)[_i]), (PG8_LAS unsigned*)(lds + (bufoff) + ldsw + _i * 8192), 16, 0, 0); } while (0)
; #define PG8_LDA(dst, b, h) do { _Pragma("unroll") for (int m = 0; m < 4; ++m) _Pragma("unroll") for (int k = 0; k < 2; ++k) dst[m][k] = *(const PG8_LAS bf16x8*)(lds + PG8_SA(b, h) + aoff + m * 2048 + k * 1024); } while (0)
; #define PG8_LDB(dst, b, h) do { _Pragma("unroll") for (int n = 0; n < 2; ++n) _Pragma("unroll") for (int k = 0; k < 2; ++k) dst[n][k] = *(const PG8_LAS bf16x8*)(lds + PG8_SB(b, h) + boff + n * 2048 + k * 1024); } while (0)
; #define PG8_MMA(ai, bj, At, Bt) do { __builtin_amdgcn_s_setprio(1); _Pragma("unroll") for (int m = 0; m < 4; ++m) _Pragma("unroll") for (int n = 0; n < 2; ++n) _Pragma("unroll") for (int k = 0; k < 2; ++k) \
;         acc[ai][bj][m][n] = __builtin_amdgcn_mfma_f32_16x16x32_bf16(Bt[n][k], At[m][k], acc[ai][bj][m][n], 0, 0, 0); __builtin_amdgcn_s_setprio(0); } while (0)
; #define PG8_WAIT_V(n) asm volatile("s_waitcnt vmcnt(" #n ")" ::: "memory")
; #define PG8_WAIT_L(n) asm volatile("s_waitcnt lgkmcnt(" #n ")" ::: "memory")
; #define PG8_BAR __builtin_amdgcn_s_barrier()
; #define PG8_SCHED __builtin_amdgcn_sched_barrier(0)
; template <class Epi, class Sched, bool ALIGN_EPI = false, bool SP2 = false>
; __device__ __forceinline__ void gemm_phase(PG8_LAS unsigned char* lds, const Gemm g, const Sched& S, const Epi& E) {
;     ...
;             const char* a2 = last ? nA : cA + (size_t)(t + 2) * kstep; const char* b2 = last ? nB : cB + (size_t)(t + 2) * kstep;
;             const char* a3 = a2 + kstep; const char* b3 = b2 + kstep;
;             if (last && has_next) S.a_ready(nxt);
;             if constexpr (SP2) {
;             PG8_LDB(B0, 0, 0); PG8_LDB(B1, 0, 1); PG8_SCHED; PG8_LDA(At, 0, 0); PG8_STAGE(PG8_SA(1, 1), a1 + hstep, voffA);
;             PG8_WAIT_V(8); PG8_WAIT_L(0); PG8_BAR; PG8_MMA(0, 0, At, B0); PG8_MMA(0, 1, At, B1); PG8_BAR; PG8_SCHED;
;             PG8_LDA(At, 0, 1); PG8_STAGE(PG8_SB(0, 0), b2, voffB); PG8_STAGE(PG8_SB(0, 1), b2 + hstep, voffB); PG8_STAGE(PG8_SA(0, 0), a2, voffA);
;             PG8_WAIT_V(8); PG8_WAIT_L(0); PG8_BAR; PG8_MMA(1, 0, At, B0); PG8_MMA(1, 1, At, B1); PG8_BAR; PG8_SCHED;
	s_add_u32 s53, s18, 0xfffc0080
	s_addc_u32 s60, s19, -1
	s_add_i32 s64, 0, 0x10000
	s_cmp_eq_u32 s52, 12
	s_cselect_b32 s63, s30, s60
	s_cselect_b32 s62, s31, s53
	s_cselect_b32 s61, s34, s47
	s_cselect_b32 s60, s35, s45
	s_add_i32 s53, 0, 0x14000
	v_add_u32_e32 v134, s64, v239
	v_add_u32_e32 v158, s53, v239
	ds_read_b128 v[122:125], v134
	ds_read_b128 v[126:129], v134 offset:1024
	ds_read_b128 v[130:133], v134 offset:2048
	ds_read_b128 v[134:137], v134 offset:3072
	ds_read_b128 v[138:141], v158
	ds_read_b128 v[142:145], v158 offset:1024
	ds_read_b128 v[146:149], v158 offset:2048
	ds_read_b128 v[158:161], v158 offset:3072
	v_lshl_add_u64 v[212:213], s[18:19], 0, v[204:205]
	s_add_i32 m0, s25, 0xc000
	ds_read_b128 v[162:165], v241
	ds_read_b128 v[166:169], v241 offset:1024
	ds_read_b128 v[170:173], v241 offset:2048
	ds_read_b128 v[174:177], v241 offset:3072
	ds_read_b128 v[178:181], v241 offset:4096
	ds_read_b128 v[182:185], v241 offset:5120
	ds_read_b128 v[186:189], v241 offset:6144
	ds_read_b128 v[208:211], v241 offset:7168
	global_load_lds_dwordx4 v[212:213], off
	v_lshl_add_u64 v[212:213], s[18:19], 0, v[206:207]
	s_add_i32 m0, s25, 0xe000
	s_nop 0
	global_load_lds_dwordx4 v[212:213], off
	s_waitcnt vmcnt(8)
	s_waitcnt lgkmcnt(0)
	s_barrier
	s_setprio 1
	s_waitcnt lgkmcnt(0)
	v_mfma_f32_16x16x32_bf16 v[154:157], v[122:125], v[162:165], 0
	v_mfma_f32_16x16x32_bf16 v[150:153], v[130:133], v[162:165], 0
	v_mfma_f32_16x16x32_bf16 v[110:113], v[122:125], v[170:173], 0
	v_mfma_f32_16x16x32_bf16 v[106:109], v[130:133], v[170:173], 0
	v_mfma_f32_16x16x32_bf16 v[94:97], v[122:125], v[178:181], 0
	v_mfma_f32_16x16x32_bf16 v[90:93], v[130:133], v[178:181], 0
	v_mfma_f32_16x16x32_bf16 v[78:81], v[122:125], v[186:189], 0
	v_mfma_f32_16x16x32_bf16 v[74:77], v[130:133], v[186:189], 0
	v_mfma_f32_16x16x32_bf16 v[154:157], v[126:129], v[166:169], v[154:157]
	v_mfma_f32_16x16x32_bf16 v[150:153], v[134:137], v[166:169], v[150:153]
	v_mfma_f32_16x16x32_bf16 v[110:113], v[126:129], v[174:177], v[110:113]
	v_mfma_f32_16x16x32_bf16 v[106:109], v[134:137], v[174:177], v[106:109]
	v_mfma_f32_16x16x32_bf16 v[94:97], v[126:129], v[182:185], v[94:97]
	v_mfma_f32_16x16x32_bf16 v[90:93], v[134:137], v[182:185], v[90:93]
	v_mfma_f32_16x16x32_bf16 v[78:81], v[126:129], v[208:211], v[78:81]
	v_mfma_f32_16x16x32_bf16 v[74:77], v[134:137], v[208:211], v[74:77]
	s_setprio 0
	s_setprio 1
	v_mfma_f32_16x16x32_bf16 v[118:121], v[138:141], v[162:165], 0
	v_mfma_f32_16x16x32_bf16 v[114:117], v[146:149], v[162:165], 0
	v_mfma_f32_16x16x32_bf16 v[102:105], v[138:141], v[170:173], 0
	v_mfma_f32_16x16x32_bf16 v[98:101], v[146:149], v[170:173], 0
	v_mfma_f32_16x16x32_bf16 v[86:89], v[138:141], v[178:181], 0
	v_mfma_f32_16x16x32_bf16 v[82:85], v[146:149], v[178:181], 0
	v_mfma_f32_16x16x32_bf16 v[70:73], v[138:141], v[186:189], 0
	v_mfma_f32_16x16x32_bf16 v[66:69], v[146:149], v[186:189], 0
	v_mfma_f32_16x16x32_bf16 v[118:121], v[142:145], v[166:169], v[118:121]
	v_mfma_f32_16x16x32_bf16 v[114:117], v[158:161], v[166:169], v[114:117]
	v_mfma_f32_16x16x32_bf16 v[102:105], v[142:145], v[174:177], v[102:105]
	v_mfma_f32_16x16x32_bf16 v[98:101], v[158:161], v[174:177], v[98:101]
	v_mfma_f32_16x16x32_bf16 v[86:89], v[142:145], v[182:185], v[86:89]
	v_mfma_f32_16x16x32_bf16 v[82:85], v[158:161], v[182:185], v[82:85]
	v_mfma_f32_16x16x32_bf16 v[70:73], v[142:145], v[208:211], v[70:73]
	v_mfma_f32_16x16x32_bf16 v[66:69], v[158:161], v[208:211], v[66:69]
	s_setprio 0
	s_barrier
	s_add_i32 s64, s64, s24
	v_lshl_add_u64 v[212:213], s[60:61], 0, v[0:1]
	s_mov_b32 m0, s64
	ds_read_b128 v[162:165], v241 offset:16384
	ds_read_b128 v[166:169], v241 offset:17408
	ds_read_b128 v[170:173], v241 offset:18432
	ds_read_b128 v[174:177], v241 offset:19456
	ds_read_b128 v[178:181], v241 offset:20480
	ds_read_b128 v[182:185], v241 offset:21504
	ds_read_b128 v[186:189], v241 offset:22528
	ds_read_b128 v[208:211], v241 offset:23552
	global_load_lds_dwordx4 v[212:213], off
	s_add_i32 m0, s64, 0x2000
	s_add_u32 s64, s60, 0x40000
	v_lshl_add_u64 v[214:215], s[60:61], 0, v[198:199]
	s_addc_u32 s65, s61, 0
	s_add_i32 s53, s53, s24
	global_load_lds_dwordx4 v[214:215], off
	v_lshl_add_u64 v[216:217], s[64:65], 0, v[0:1]
	s_mov_b32 m0, s53
	v_lshl_add_u64 v[218:219], s[62:63], 0, v[196:197]
	global_load_lds_dwordx4 v[216:217], off
	v_lshl_add_u64 v[216:217], s[64:65], 0, v[198:199]
	s_add_i32 m0, s53, 0x2000
	s_nop 0
	global_load_lds_dwordx4 v[216:217], off
	v_lshl_add_u64 v[216:217], s[62:63], 0, v[194:195]
	s_mov_b32 m0, s25
	s_nop 0
	global_load_lds_dwordx4 v[216:217], off
	s_mov_b32 m0, s26
	s_nop 0
	global_load_lds_dwordx4 v[218:219], off
	s_waitcnt vmcnt(8)
	s_waitcnt lgkmcnt(0)
	s_barrier
; #define PG8_STAGE(bufoff, gbase, voff) do { _Pragma("unroll") for (int _i = 0; _i < 2; ++_i) \
;         __builtin_amdgcn_global_load_lds((const unsigned*)((const char*)(gbase) + (voff)[_i]), (PG8_LAS unsigned*)(lds + (bufoff) + ldsw + _i * 8192), 16, 0, 0); } while (0)
; #define PG8_LDA(dst, b, h) do { _Pragma("unroll") for (int m = 0; m < 4; ++m) _Pragma("unroll") for (int k = 0; k < 2; ++k) dst[m][k] = *(const PG8_LAS bf16x8*)(lds + PG8_SA(b, h) + aoff + m * 2048 + k * 1024); } while (0)
; #define PG8_LDB(dst, b, h) do { _Pragma("unroll") for (int n = 0; n < 2; ++n) _Pragma("unroll") for (int k = 0; k < 2; ++k) dst[n][k] = *(const PG8_LAS bf16x8*)(lds + PG8_SB(b, h) + boff + n * 2048 + k * 1024); } while (0)
; #define PG8_MMA(ai, bj, At, Bt) do { __builtin_amdgcn_s_setprio(1); _Pragma("unroll") for (int m = 0; m < 4; ++m) _Pragma("unroll") for (int n = 0; n < 2; ++n) _Pragma("unroll") for (int k = 0; k < 2; ++k) \
;         acc[ai][bj][m][n] = __builtin_amdgcn_mfma_f32_16x16x32_bf16(Bt[n][k], At[m][k], acc[ai][bj][m][n], 0, 0, 0); __builtin_amdgcn_s_setprio(0); } while (0)
; #define PG8_WAIT_V(n) asm volatile("s_waitcnt vmcnt(" #n ")" ::: "memory")
; #define PG8_WAIT_L(n) asm volatile("s_waitcnt lgkmcnt(" #n ")" ::: "memory")
; #define PG8_BAR __builtin_amdgcn_s_barrier()
; #define PG8_SCHED __builtin_amdgcn_sched_barrier(0)
; template <class Epi, class Sched, bool ALIGN_EPI = false, bool SP2 = false>
; __device__ __forceinline__ void gemm_phase(PG8_LAS unsigned char* lds, const Gemm g, const Sched& S, const Epi& E) {
;     ...
;             PG8_WAIT_V(8); PG8_WAIT_L(0); PG8_BAR; PG8_MMA(1, 0, At, B0); PG8_MMA(1, 1, At, B1); PG8_BAR; PG8_SCHED;
;             PG8_LDB(B0, 1, 0); PG8_LDB(B1, 1, 1); PG8_SCHED; PG8_LDA(At, 1, 0); PG8_STAGE(PG8_SA(0, 1), a2 + hstep, voffA);
;             PG8_WAIT_V(8); PG8_WAIT_L(0); PG8_BAR; PG8_MMA(0, 0, At, B0); PG8_MMA(0, 1, At, B1); PG8_BAR; PG8_SCHED;
	s_setprio 1
	s_waitcnt lgkmcnt(0)
	v_mfma_f32_16x16x32_bf16 v[62:65], v[122:125], v[162:165], 0
	v_mfma_f32_16x16x32_bf16 v[58:61], v[130:133], v[162:165], 0
	v_mfma_f32_16x16x32_bf16 v[46:49], v[122:125], v[170:173], 0
	v_mfma_f32_16x16x32_bf16 v[42:45], v[130:133], v[170:173], 0
	v_mfma_f32_16x16x32_bf16 v[30:33], v[122:125], v[178:181], 0
	v_mfma_f32_16x16x32_bf16 v[26:29], v[130:133], v[178:181], 0
	v_mfma_f32_16x16x32_bf16 v[14:17], v[122:125], v[186:189], 0
	v_mfma_f32_16x16x32_bf16 v[10:13], v[130:133], v[186:189], 0
	v_mfma_f32_16x16x32_bf16 v[62:65], v[126:129], v[166:169], v[62:65]
	v_mfma_f32_16x16x32_bf16 v[58:61], v[134:137], v[166:169], v[58:61]
	v_mfma_f32_16x16x32_bf16 v[46:49], v[126:129], v[174:177], v[46:49]
	v_mfma_f32_16x16x32_bf16 v[42:45], v[134:137], v[174:177], v[42:45]
	v_mfma_f32_16x16x32_bf16 v[30:33], v[126:129], v[182:185], v[30:33]
	v_mfma_f32_16x16x32_bf16 v[26:29], v[134:137], v[182:185], v[26:29]
	v_mfma_f32_16x16x32_bf16 v[14:17], v[126:129], v[208:211], v[14:17]
	v_mfma_f32_16x16x32_bf16 v[10:13], v[134:137], v[208:211], v[10:13]
	s_setprio 0
	s_setprio 1
	v_mfma_f32_16x16x32_bf16 v[54:57], v[138:141], v[162:165], 0
	v_mfma_f32_16x16x32_bf16 v[50:53], v[146:149], v[162:165], 0
	v_mfma_f32_16x16x32_bf16 v[38:41], v[138:141], v[170:173], 0
	v_mfma_f32_16x16x32_bf16 v[34:37], v[146:149], v[170:173], 0
	v_mfma_f32_16x16x32_bf16 v[22:25], v[138:141], v[178:181], 0
	v_mfma_f32_16x16x32_bf16 v[18:21], v[146:149], v[178:181], 0
	v_mfma_f32_16x16x32_bf16 v[6:9], v[138:141], v[186:189], 0
	v_mfma_f32_16x16x32_bf16 v[2:5], v[146:149], v[186:189], 0
	v_mfma_f32_16x16x32_bf16 v[54:57], v[142:145], v[166:169], v[54:57]
	v_mfma_f32_16x16x32_bf16 v[50:53], v[158:161], v[166:169], v[50:53]
	v_mfma_f32_16x16x32_bf16 v[38:41], v[142:145], v[174:177], v[38:41]
	v_mfma_f32_16x16x32_bf16 v[34:37], v[158:161], v[174:177], v[34:37]
	v_mfma_f32_16x16x32_bf16 v[22:25], v[142:145], v[182:185], v[22:25]
	v_mfma_f32_16x16x32_bf16 v[18:21], v[158:161], v[182:185], v[18:21]
	v_mfma_f32_16x16x32_bf16 v[6:9], v[142:145], v[208:211], v[6:9]
	v_mfma_f32_16x16x32_bf16 v[2:5], v[158:161], v[208:211], v[2:5]
	s_setprio 0
	s_barrier
	s_add_i32 s53, 0, 0x18000
	s_add_i32 s64, 0, 0x1c000
	v_add_u32_e32 v134, s53, v239
	v_add_u32_e32 v158, s64, v239
	ds_read_b128 v[122:125], v134
	ds_read_b128 v[126:129], v134 offset:1024
	ds_read_b128 v[130:133], v134 offset:2048
	ds_read_b128 v[134:137], v134 offset:3072
	ds_read_b128 v[138:141], v158
	ds_read_b128 v[142:145], v158 offset:1024
	ds_read_b128 v[146:149], v158 offset:2048
	ds_read_b128 v[158:161], v158 offset:3072
	s_add_u32 s62, s62, 0x40000
	s_addc_u32 s63, s63, 0
	s_mov_b32 m0, s27
	v_lshl_add_u64 v[220:221], s[62:63], 0, v[194:195]
	ds_read_b128 v[162:165], v241 offset:32768
	ds_read_b128 v[166:169], v241 offset:33792
	ds_read_b128 v[170:173], v241 offset:34816
	ds_read_b128 v[174:177], v241 offset:35840
	ds_read_b128 v[178:181], v241 offset:36864
	ds_read_b128 v[182:185], v241 offset:37888
	ds_read_b128 v[186:189], v241 offset:38912
	ds_read_b128 v[208:211], v241 offset:39936
	global_load_lds_dwordx4 v[220:221], off
	v_lshl_add_u64 v[220:221], s[62:63], 0, v[196:197]
	s_mov_b32 m0, s28
	s_nop 0
	global_load_lds_dwordx4 v[220:221], off
	s_waitcnt vmcnt(8)
	s_waitcnt lgkmcnt(0)
	s_barrier
	s_setprio 1
	s_waitcnt lgkmcnt(0)
	v_mfma_f32_16x16x32_bf16 v[154:157], v[122:125], v[162:165], v[154:157]
	v_mfma_f32_16x16x32_bf16 v[150:153], v[130:133], v[162:165], v[150:153]
	v_mfma_f32_16x16x32_bf16 v[110:113], v[122:125], v[170:173], v[110:113]
	v_mfma_f32_16x16x32_bf16 v[106:109], v[130:133], v[170:173], v[106:109]
	v_mfma_f32_16x16x32_bf16 v[94:97], v[122:125], v[178:181], v[94:97]
	v_mfma_f32_16x16x32_bf16 v[90:93], v[130:133], v[178:181], v[90:93]
	v_mfma_f32_16x16x32_bf16 v[78:81], v[122:125], v[186:189], v[78:81]
	v_mfma_f32_16x16x32_bf16 v[74:77], v[130:133], v[186:189], v[74:77]
	v_mfma_f32_16x16x32_bf16 v[154:157], v[126:129], v[166:169], v[154:157]
	v_mfma_f32_16x16x32_bf16 v[150:153], v[134:137], v[166:169], v[150:153]
	v_mfma_f32_16x16x32_bf16 v[110:113], v[126:129], v[174:177], v[110:113]
	v_mfma_f32_16x16x32_bf16 v[106:109], v[134:137], v[174:177], v[106:109]
	v_mfma_f32_16x16x32_bf16 v[94:97], v[126:129], v[182:185], v[94:97]
	v_mfma_f32_16x16x32_bf16 v[90:93], v[134:137], v[182:185], v[90:93]
	v_mfma_f32_16x16x32_bf16 v[78:81], v[126:129], v[208:211], v[78:81]
	v_mfma_f32_16x16x32_bf16 v[74:77], v[134:137], v[208:211], v[74:77]
	s_setprio 0
	s_setprio 1
	v_mfma_f32_16x16x32_bf16 v[118:121], v[138:141], v[162:165], v[118:121]
	v_mfma_f32_16x16x32_bf16 v[114:117], v[146:149], v[162:165], v[114:117]
	v_mfma_f32_16x16x32_bf16 v[102:105], v[138:141], v[170:173], v[102:105]
	v_mfma_f32_16x16x32_bf16 v[98:101], v[146:149], v[170:173], v[98:101]
	v_mfma_f32_16x16x32_bf16 v[86:89], v[138:141], v[178:181], v[86:89]
	v_mfma_f32_16x16x32_bf16 v[82:85], v[146:149], v[178:181], v[82:85]
	v_mfma_f32_16x16x32_bf16 v[70:73], v[138:141], v[186:189], v[70:73]
	v_mfma_f32_16x16x32_bf16 v[66:69], v[146:149], v[186:189], v[66:69]
	v_mfma_f32_16x16x32_bf16 v[118:121], v[142:145], v[166:169], v[118:121]
	v_mfma_f32_16x16x32_bf16 v[114:117], v[158:161], v[166:169], v[114:117]
	v_mfma_f32_16x16x32_bf16 v[102:105], v[142:145], v[174:177], v[102:105]
	v_mfma_f32_16x16x32_bf16 v[98:101], v[158:161], v[174:177], v[98:101]
	v_mfma_f32_16x16x32_bf16 v[86:89], v[142:145], v[182:185], v[86:89]
	v_mfma_f32_16x16x32_bf16 v[82:85], v[158:161], v[182:185], v[82:85]
	v_mfma_f32_16x16x32_bf16 v[70:73], v[142:145], v[208:211], v[70:73]
	v_mfma_f32_16x16x32_bf16 v[66:69], v[158:161], v[208:211], v[66:69]
	s_setprio 0
	s_barrier
; #define PG8_STAGE(bufoff, gbase, voff) do { _Pragma("unroll") for (int _i = 0; _i < 2; ++_i) \
;         __builtin_amdgcn_global_load_lds((const unsigned*)((const char*)(gbase) + (voff)[_i]), (PG8_LAS unsigned*)(lds + (bufoff) + ldsw + _i * 8192), 16, 0, 0); } while (0)
; #define PG8_LDA(dst, b, h) do { _Pragma("unroll") for (int m = 0; m < 4; ++m) _Pragma("unroll") for (int k = 0; k < 2; ++k) dst[m][k] = *(const PG8_LAS bf16x8*)(lds + PG8_SA(b, h) + aoff + m * 2048 + k * 1024); } while (0)
; #define PG8_MMA(ai, bj, At, Bt) do { __builtin_amdgcn_s_setprio(1); _Pragma("unroll") for (int m = 0; m < 4; ++m) _Pragma("unroll") for (int n = 0; n < 2; ++n) _Pragma("unroll") for (int k = 0; k < 2; ++k) \
;         acc[ai][bj][m][n] = __builtin_amdgcn_mfma_f32_16x16x32_bf16(Bt[n][k], At[m][k], acc[ai][bj][m][n], 0, 0, 0); __builtin_amdgcn_s_setprio(0); } while (0)
; #define PG8_WAIT_V(n) asm volatile("s_waitcnt vmcnt(" #n ")" ::: "memory")
; #define PG8_WAIT_L(n) asm volatile("s_waitcnt lgkmcnt(" #n ")" ::: "memory")
; #define PG8_BAR __builtin_amdgcn_s_barrier()
; #define PG8_SCHED __builtin_amdgcn_sched_barrier(0)
; template <class Epi, class Sched, bool ALIGN_EPI = false, bool SP2 = false>
; __device__ __forceinline__ void gemm_phase(PG8_LAS unsigned char* lds, const Gemm g, const Sched& S, const Epi& E) {
;     ...
;             PG8_LDA(At, 1, 1); PG8_STAGE(PG8_SB(1, 0), b3, voffB); PG8_STAGE(PG8_SB(1, 1), b3 + hstep, voffB); PG8_STAGE(PG8_SA(1, 0), a3, voffA);
;             PG8_WAIT_V(8); PG8_WAIT_L(0); PG8_BAR; PG8_MMA(1, 0, At, B0); PG8_MMA(1, 1, At, B1); PG8_BAR; PG8_SCHED;
	s_add_i32 s53, s53, s24
	v_lshl_add_u64 v[212:213], v[212:213], 0, s[8:9]
	s_mov_b32 m0, s53
	ds_read_b128 v[162:165], v241 offset:49152
	ds_read_b128 v[166:169], v241 offset:50176
	ds_read_b128 v[170:173], v241 offset:51200
	ds_read_b128 v[174:177], v241 offset:52224
	ds_read_b128 v[178:181], v241 offset:53248
	ds_read_b128 v[182:185], v241 offset:54272
	ds_read_b128 v[186:189], v241 offset:55296
	ds_read_b128 v[208:211], v241 offset:56320
	global_load_lds_dwordx4 v[212:213], off
	s_add_i32 m0, s53, 0x2000
	s_add_u32 s60, s60, 0x40080
	v_lshl_add_u64 v[212:213], v[214:215], 0, s[8:9]
	s_addc_u32 s61, s61, 0
	s_add_i32 s53, s64, s24
	global_load_lds_dwordx4 v[212:213], off
	v_lshl_add_u64 v[212:213], s[60:61], 0, v[0:1]
	s_mov_b32 m0, s53
	s_nop 0
	global_load_lds_dwordx4 v[212:213], off
	v_lshl_add_u64 v[212:213], s[60:61], 0, v[198:199]
	s_add_i32 m0, s53, 0x2000
	s_nop 0
	global_load_lds_dwordx4 v[212:213], off
	v_lshl_add_u64 v[212:213], v[216:217], 0, s[8:9]
	s_mov_b32 m0, s29
	s_nop 0
	global_load_lds_dwordx4 v[212:213], off
	v_lshl_add_u64 v[212:213], v[218:219], 0, s[8:9]
	s_mov_b32 m0, s57
	s_nop 0
	global_load_lds_dwordx4 v[212:213], off
	s_waitcnt vmcnt(8)
	s_waitcnt lgkmcnt(0)
	s_barrier
	s_setprio 1
	s_waitcnt lgkmcnt(0)
	v_mfma_f32_16x16x32_bf16 v[62:65], v[122:125], v[162:165], v[62:65]
	v_mfma_f32_16x16x32_bf16 v[58:61], v[130:133], v[162:165], v[58:61]
	v_mfma_f32_16x16x32_bf16 v[46:49], v[122:125], v[170:173], v[46:49]
	v_mfma_f32_16x16x32_bf16 v[42:45], v[130:133], v[170:173], v[42:45]
	v_mfma_f32_16x16x32_bf16 v[30:33], v[122:125], v[178:181], v[30:33]
	v_mfma_f32_16x16x32_bf16 v[26:29], v[130:133], v[178:181], v[26:29]
	v_mfma_f32_16x16x32_bf16 v[14:17], v[122:125], v[186:189], v[14:17]
	v_mfma_f32_16x16x32_bf16 v[10:13], v[130:133], v[186:189], v[10:13]
	v_mfma_f32_16x16x32_bf16 v[62:65], v[126:129], v[166:169], v[62:65]
	v_mfma_f32_16x16x32_bf16 v[58:61], v[134:137], v[166:169], v[58:61]
	v_mfma_f32_16x16x32_bf16 v[46:49], v[126:129], v[174:177], v[46:49]
	v_mfma_f32_16x16x32_bf16 v[42:45], v[134:137], v[174:177], v[42:45]
	v_mfma_f32_16x16x32_bf16 v[30:33], v[126:129], v[182:185], v[30:33]
	v_mfma_f32_16x16x32_bf16 v[26:29], v[134:137], v[182:185], v[26:29]
	v_mfma_f32_16x16x32_bf16 v[14:17], v[126:129], v[208:211], v[14:17]
	v_mfma_f32_16x16x32_bf16 v[10:13], v[134:137], v[208:211], v[10:13]
	s_setprio 0
	s_setprio 1
	v_mfma_f32_16x16x32_bf16 v[54:57], v[138:141], v[162:165], v[54:57]
	v_mfma_f32_16x16x32_bf16 v[50:53], v[146:149], v[162:165], v[50:53]
	v_mfma_f32_16x16x32_bf16 v[38:41], v[138:141], v[170:173], v[38:41]
	v_mfma_f32_16x16x32_bf16 v[34:37], v[146:149], v[170:173], v[34:37]
	v_mfma_f32_16x16x32_bf16 v[22:25], v[138:141], v[178:181], v[22:25]
	v_mfma_f32_16x16x32_bf16 v[18:21], v[146:149], v[178:181], v[18:21]
	v_mfma_f32_16x16x32_bf16 v[6:9], v[138:141], v[186:189], v[6:9]
	v_mfma_f32_16x16x32_bf16 v[2:5], v[146:149], v[186:189], v[2:5]
	v_mfma_f32_16x16x32_bf16 v[54:57], v[142:145], v[166:169], v[54:57]
	v_mfma_f32_16x16x32_bf16 v[50:53], v[158:161], v[166:169], v[50:53]
	v_mfma_f32_16x16x32_bf16 v[38:41], v[142:145], v[174:177], v[38:41]
	v_mfma_f32_16x16x32_bf16 v[34:37], v[158:161], v[174:177], v[34:37]
	v_mfma_f32_16x16x32_bf16 v[22:25], v[142:145], v[182:185], v[22:25]
	v_mfma_f32_16x16x32_bf16 v[18:21], v[158:161], v[182:185], v[18:21]
	v_mfma_f32_16x16x32_bf16 v[6:9], v[142:145], v[208:211], v[6:9]
	v_mfma_f32_16x16x32_bf16 v[2:5], v[158:161], v[208:211], v[2:5]
	s_setprio 0
	s_barrier
	s_add_i32 s52, s52, 2
	s_add_u32 s18, s18, 0x100
	s_addc_u32 s19, s19, 0
	s_add_u32 s45, s45, 0x100
	s_addc_u32 s47, s47, 0
	s_cmp_gt_u32 s52, 13

; template <class Epi, class Sched, bool ALIGN_EPI = false, bool SP2 = false>
; __device__ __forceinline__ void gemm_phase(PG8_LAS unsigned char* lds, const Gemm g, const Sched& S, const Epi& E) {
;     ...
;         const bool has_next = S.next(ui + 1, nxt);
;         const char* nA = has_next ? (const char*)g.A + (size_t)nxt.pm * tstep : cA; const char* nB = has_next ? (const char*)g.Bt + (size_t)nxt.pn * tstep : cB;
;         for (int t = 0; t < nt; t += 2) {
.LBB0_521:
	s_ashr_i32 s45, s44, 31
	s_lshl_b64 s[30:31], s[44:45], 19
	s_add_u32 s48, s98, s30
	s_addc_u32 s49, s99, s31
	s_and_b64 s[30:31], s[46:47], exec
	s_cselect_b32 s30, s49, s19
	s_cselect_b32 s31, s48, s18
	s_ashr_i32 s43, s42, 31
	s_lshl_b64 s[34:35], s[42:43], 19
	s_add_u32 s50, s68, s34
	s_addc_u32 s51, s69, s35
	s_and_b64 s[34:35], s[46:47], exec
	s_cselect_b32 s34, s51, s59
	s_cselect_b32 s35, s50, s58
	s_add_u32 s18, s18, 0x40080
	s_addc_u32 s19, s19, 0
	s_add_u32 s43, s58, 0x100

; template <class Epi, class Sched, bool ALIGN_EPI = false, bool SP2 = false>
; __device__ __forceinline__ void gemm_phase(PG8_LAS unsigned char* lds, const Gemm g, const Sched& S, const Epi& E) {
;     ...
;         for (int t = 0; t < nt; t += 2) {
;             const bool last = (t == nt - 2);
;             const char* a1 = cA + (size_t)(t + 1) * kstep;
;             const char* a2 = last ? nA : cA + (size_t)(t + 2) * kstep; const char* b2 = last ? nB : cB + (size_t)(t + 2) * kstep;
	s_addc_u32 s45, s59, 0
	s_mov_b32 s52, -2


; template <class Epi, class Sched, bool ALIGN_EPI = false, bool SP2 = false>
; __device__ __forceinline__ void gemm_phase(PG8_LAS unsigned char* lds, const Gemm g, const Sched& S, const Epi& E) {
;     ...
;     for (;;) {
;         const bool has_next = S.next(ui + 1, nxt);
;         const char* nA = has_next ? (const char*)g.A + (size_t)nxt.pm * tstep : cA; const char* nB = has_next ? (const char*)g.Bt + (size_t)nxt.pn * tstep : cB;
;         for (int t = 0; t < nt; t += 2) {
	s_waitcnt lgkmcnt(0)


; #define PG8_STAGE(bufoff, gbase, voff) do { _Pragma("unroll") for (int _i = 0; _i < 2; ++_i) \
;         __builtin_amdgcn_global_load_lds((const unsigned*)((const char*)(gbase) + (voff)[_i]), (PG8_LAS unsigned*)(lds + (bufoff) + ldsw + _i * 8192), 16, 0, 0); } while (0)
; #define PG8_LDA(dst, b, h) do { _Pragma("unroll") for (int m = 0; m < 4; ++m) _Pragma("unroll") for (int k = 0; k < 2; ++k) dst[m][k] = *(const PG8_LAS bf16x8*)(lds + PG8_SA(b, h) + aoff + m * 2048 + k * 1024); } while (0)
; #define PG8_LDB(dst, b, h) do { _Pragma("unroll") for (int n = 0; n < 2; ++n) _Pragma("unroll") for (int k = 0; k < 2; ++k) dst[n][k] = *(const PG8_LAS bf16x8*)(lds + PG8_SB(b, h) + boff + n * 2048 + k * 1024); } while (0)
; #define PG8_MMA(ai, bj, At, Bt) do { __builtin_amdgcn_s_setprio(1); _Pragma("unroll") for (int m = 0; m < 4; ++m) _Pragma("unroll") for (int n = 0; n < 2; ++n) _Pragma("unroll") for (int k = 0; k < 2; ++k) \
;         acc[ai][bj][m][n] = __builtin_amdgcn_mfma_f32_16x16x32_bf16(Bt[n][k], At[m][k], acc[ai][bj][m][n], 0, 0, 0); __builtin_amdgcn_s_setprio(0); } while (0)
; #define PG8_WAIT_V(n) asm volatile("s_waitcnt vmcnt(" #n ")" ::: "memory")
; #define PG8_WAIT_L(n) asm volatile("s_waitcnt lgkmcnt(" #n ")" ::: "memory")
; #define PG8_BAR __builtin_amdgcn_s_barrier()
; #define PG8_SCHED __builtin_amdgcn_sched_barrier(0)
; template <class Epi, class Sched, bool ALIGN_EPI = false, bool SP2 = false>
; __device__ __forceinline__ void gemm_phase(PG8_LAS unsigned char* lds, const Gemm g, const Sched& S, const Epi& E) {
;     ...
;             const char* a2 = last ? nA : cA + (size_t)(t + 2) * kstep; const char* b2 = last ? nB : cB + (size_t)(t + 2) * kstep;
;             const char* a3 = a2 + kstep; const char* b3 = b2 + kstep;
;             if (last && has_next) S.a_ready(nxt);
;             if constexpr (SP2) {
;             PG8_LDB(B0, 0, 0); PG8_LDB(B1, 0, 1); PG8_SCHED; PG8_LDA(At, 0, 0); PG8_STAGE(PG8_SA(1, 1), a1 + hstep, voffA);
;             PG8_WAIT_V(8); PG8_WAIT_L(0); PG8_BAR; PG8_MMA(0, 0, At, B0); PG8_MMA(0, 1, At, B1); PG8_BAR; PG8_SCHED;
;             PG8_LDA(At, 0, 1); PG8_STAGE(PG8_SB(0, 0), b2, voffB); PG8_STAGE(PG8_SB(0, 1), b2 + hstep, voffB); PG8_STAGE(PG8_SA(0, 0), a2, voffA);
;             PG8_WAIT_V(8); PG8_WAIT_L(0); PG8_BAR; PG8_MMA(1, 0, At, B0); PG8_MMA(1, 1, At, B1); PG8_BAR; PG8_SCHED;
	s_add_u32 s53, s18, 0xfffc0080
	s_addc_u32 s58, s19, -1
	s_add_i32 s62, 0, 0x10000
	s_cmp_eq_u32 s52, 12
	s_cselect_b32 s61, s30, s58
	s_cselect_b32 s60, s31, s53
	s_cselect_b32 s59, s34, s45
	s_cselect_b32 s58, s35, s43
	s_add_i32 s53, 0, 0x14000
	v_add_u32_e32 v156, s62, v149
	v_add_u32_e32 v172, s53, v149
	ds_read_b128 v[140:143], v156
	ds_read_b128 v[144:147], v156 offset:1024
	ds_read_b128 v[152:155], v156 offset:2048
	ds_read_b128 v[156:159], v156 offset:3072
	ds_read_b128 v[160:163], v172
	ds_read_b128 v[164:167], v172 offset:1024
	ds_read_b128 v[168:171], v172 offset:2048
	ds_read_b128 v[172:175], v172 offset:3072
	v_lshl_add_u64 v[188:189], s[18:19], 0, v[136:137]
	s_add_i32 m0, s25, 0xc000
	ds_read_b128 v[176:179], v151
	ds_read_b128 v[180:183], v151 offset:1024
	ds_read_b128 v[184:187], v151 offset:2048
	ds_read_b128 v[194:197], v151 offset:3072
	ds_read_b128 v[198:201], v151 offset:4096
	ds_read_b128 v[202:205], v151 offset:5120
	ds_read_b128 v[206:209], v151 offset:6144
	ds_read_b128 v[210:213], v151 offset:7168
	global_load_lds_dwordx4 v[188:189], off
	v_lshl_add_u64 v[188:189], s[18:19], 0, v[138:139]
	s_add_i32 m0, s25, 0xe000
	s_nop 0
	global_load_lds_dwordx4 v[188:189], off
	s_waitcnt vmcnt(8)
	s_waitcnt lgkmcnt(0)
	s_barrier
	s_setprio 1
	s_waitcnt lgkmcnt(0)
	v_mfma_f32_16x16x32_bf16 v[126:129], v[140:143], v[176:179], 0
	v_mfma_f32_16x16x32_bf16 v[122:125], v[152:155], v[176:179], 0
	v_mfma_f32_16x16x32_bf16 v[118:121], v[140:143], v[184:187], 0
	v_mfma_f32_16x16x32_bf16 v[110:113], v[152:155], v[184:187], 0
	v_mfma_f32_16x16x32_bf16 v[94:97], v[140:143], v[198:201], 0
	v_mfma_f32_16x16x32_bf16 v[90:93], v[152:155], v[198:201], 0
	v_mfma_f32_16x16x32_bf16 v[78:81], v[140:143], v[206:209], 0
	v_mfma_f32_16x16x32_bf16 v[74:77], v[152:155], v[206:209], 0
	v_mfma_f32_16x16x32_bf16 v[126:129], v[144:147], v[180:183], v[126:129]
	v_mfma_f32_16x16x32_bf16 v[122:125], v[156:159], v[180:183], v[122:125]
	v_mfma_f32_16x16x32_bf16 v[118:121], v[144:147], v[194:197], v[118:121]
	v_mfma_f32_16x16x32_bf16 v[110:113], v[156:159], v[194:197], v[110:113]
	v_mfma_f32_16x16x32_bf16 v[94:97], v[144:147], v[202:205], v[94:97]
	v_mfma_f32_16x16x32_bf16 v[90:93], v[156:159], v[202:205], v[90:93]
	v_mfma_f32_16x16x32_bf16 v[78:81], v[144:147], v[210:213], v[78:81]
	v_mfma_f32_16x16x32_bf16 v[74:77], v[156:159], v[210:213], v[74:77]
	s_setprio 0
	s_setprio 1
	v_mfma_f32_16x16x32_bf16 v[114:117], v[160:163], v[176:179], 0
	v_mfma_f32_16x16x32_bf16 v[106:109], v[168:171], v[176:179], 0
	v_mfma_f32_16x16x32_bf16 v[102:105], v[160:163], v[184:187], 0
	v_mfma_f32_16x16x32_bf16 v[98:101], v[168:171], v[184:187], 0
	v_mfma_f32_16x16x32_bf16 v[86:89], v[160:163], v[198:201], 0
	v_mfma_f32_16x16x32_bf16 v[82:85], v[168:171], v[198:201], 0
	v_mfma_f32_16x16x32_bf16 v[70:73], v[160:163], v[206:209], 0
	v_mfma_f32_16x16x32_bf16 v[66:69], v[168:171], v[206:209], 0
	v_mfma_f32_16x16x32_bf16 v[114:117], v[164:167], v[180:183], v[114:117]
	v_mfma_f32_16x16x32_bf16 v[106:109], v[172:175], v[180:183], v[106:109]
	v_mfma_f32_16x16x32_bf16 v[102:105], v[164:167], v[194:197], v[102:105]
	v_mfma_f32_16x16x32_bf16 v[98:101], v[172:175], v[194:197], v[98:101]
	v_mfma_f32_16x16x32_bf16 v[86:89], v[164:167], v[202:205], v[86:89]
	v_mfma_f32_16x16x32_bf16 v[82:85], v[172:175], v[202:205], v[82:85]
	v_mfma_f32_16x16x32_bf16 v[70:73], v[164:167], v[210:213], v[70:73]
	v_mfma_f32_16x16x32_bf16 v[66:69], v[172:175], v[210:213], v[66:69]
	s_setprio 0
	s_barrier
	s_add_i32 s62, s62, s24
	v_lshl_add_u64 v[188:189], s[58:59], 0, v[0:1]
	s_mov_b32 m0, s62
	ds_read_b128 v[176:179], v151 offset:16384
	ds_read_b128 v[180:183], v151 offset:17408
	ds_read_b128 v[184:187], v151 offset:18432
	ds_read_b128 v[194:197], v151 offset:19456
	ds_read_b128 v[198:201], v151 offset:20480
	ds_read_b128 v[202:205], v151 offset:21504
	ds_read_b128 v[206:209], v151 offset:22528
	ds_read_b128 v[210:213], v151 offset:23552
	global_load_lds_dwordx4 v[188:189], off
	s_add_i32 m0, s62, 0x2000
	s_add_u32 s62, s58, 0x40000
	v_lshl_add_u64 v[214:215], s[58:59], 0, v[134:135]
	s_addc_u32 s63, s59, 0
	s_add_i32 s53, s53, s24
	global_load_lds_dwordx4 v[214:215], off
	v_lshl_add_u64 v[216:217], s[62:63], 0, v[0:1]
	s_mov_b32 m0, s53
	v_lshl_add_u64 v[218:219], s[60:61], 0, v[132:133]
	global_load_lds_dwordx4 v[216:217], off
	v_lshl_add_u64 v[216:217], s[62:63], 0, v[134:135]
	s_add_i32 m0, s53, 0x2000
	s_nop 0
	global_load_lds_dwordx4 v[216:217], off
	v_lshl_add_u64 v[216:217], s[60:61], 0, v[130:131]
	s_mov_b32 m0, s25
	s_nop 0
	global_load_lds_dwordx4 v[216:217], off
	s_mov_b32 m0, s26
	s_nop 0
	global_load_lds_dwordx4 v[218:219], off
	s_waitcnt vmcnt(8)
	s_waitcnt lgkmcnt(0)
	s_barrier
; #define PG8_STAGE(bufoff, gbase, voff) do { _Pragma("unroll") for (int _i = 0; _i < 2; ++_i) \
;         __builtin_amdgcn_global_load_lds((const unsigned*)((const char*)(gbase) + (voff)[_i]), (PG8_LAS unsigned*)(lds + (bufoff) + ldsw + _i * 8192), 16, 0, 0); } while (0)
; #define PG8_LDA(dst, b, h) do { _Pragma("unroll") for (int m = 0; m < 4; ++m) _Pragma("unroll") for (int k = 0; k < 2; ++k) dst[m][k] = *(const PG8_LAS bf16x8*)(lds + PG8_SA(b, h) + aoff + m * 2048 + k * 1024); } while (0)
; #define PG8_LDB(dst, b, h) do { _Pragma("unroll") for (int n = 0; n < 2; ++n) _Pragma("unroll") for (int k = 0; k < 2; ++k) dst[n][k] = *(const PG8_LAS bf16x8*)(lds + PG8_SB(b, h) + boff + n * 2048 + k * 1024); } while (0)
; #define PG8_MMA(ai, bj, At, Bt) do { __builtin_amdgcn_s_setprio(1); _Pragma("unroll") for (int m = 0; m < 4; ++m) _Pragma("unroll") for (int n = 0; n < 2; ++n) _Pragma("unroll") for (int k = 0; k < 2; ++k) \
;         acc[ai][bj][m][n] = __builtin_amdgcn_mfma_f32_16x16x32_bf16(Bt[n][k], At[m][k], acc[ai][bj][m][n], 0, 0, 0); __builtin_amdgcn_s_setprio(0); } while (0)
; #define PG8_WAIT_V(n) asm volatile("s_waitcnt vmcnt(" #n ")" ::: "memory")
; #define PG8_WAIT_L(n) asm volatile("s_waitcnt lgkmcnt(" #n ")" ::: "memory")
; #define PG8_BAR __builtin_amdgcn_s_barrier()
; #define PG8_SCHED __builtin_amdgcn_sched_barrier(0)
; template <class Epi, class Sched, bool ALIGN_EPI = false, bool SP2 = false>
; __device__ __forceinline__ void gemm_phase(PG8_LAS unsigned char* lds, const Gemm g, const Sched& S, const Epi& E) {
;     ...
;             PG8_WAIT_V(8); PG8_WAIT_L(0); PG8_BAR; PG8_MMA(1, 0, At, B0); PG8_MMA(1, 1, At, B1); PG8_BAR; PG8_SCHED;
;             PG8_LDB(B0, 1, 0); PG8_LDB(B1, 1, 1); PG8_SCHED; PG8_LDA(At, 1, 0); PG8_STAGE(PG8_SA(0, 1), a2 + hstep, voffA);
;             PG8_WAIT_V(8); PG8_WAIT_L(0); PG8_BAR; PG8_MMA(0, 0, At, B0); PG8_MMA(0, 1, At, B1); PG8_BAR; PG8_SCHED;
	s_setprio 1
	s_waitcnt lgkmcnt(0)
	v_mfma_f32_16x16x32_bf16 v[62:65], v[140:143], v[176:179], 0
	v_mfma_f32_16x16x32_bf16 v[58:61], v[152:155], v[176:179], 0
	v_mfma_f32_16x16x32_bf16 v[46:49], v[140:143], v[184:187], 0
	v_mfma_f32_16x16x32_bf16 v[42:45], v[152:155], v[184:187], 0
	v_mfma_f32_16x16x32_bf16 v[30:33], v[140:143], v[198:201], 0
	v_mfma_f32_16x16x32_bf16 v[26:29], v[152:155], v[198:201], 0
	v_mfma_f32_16x16x32_bf16 v[14:17], v[140:143], v[206:209], 0
	v_mfma_f32_16x16x32_bf16 v[10:13], v[152:155], v[206:209], 0
	v_mfma_f32_16x16x32_bf16 v[62:65], v[144:147], v[180:183], v[62:65]
	v_mfma_f32_16x16x32_bf16 v[58:61], v[156:159], v[180:183], v[58:61]
	v_mfma_f32_16x16x32_bf16 v[46:49], v[144:147], v[194:197], v[46:49]
	v_mfma_f32_16x16x32_bf16 v[42:45], v[156:159], v[194:197], v[42:45]
	v_mfma_f32_16x16x32_bf16 v[30:33], v[144:147], v[202:205], v[30:33]
	v_mfma_f32_16x16x32_bf16 v[26:29], v[156:159], v[202:205], v[26:29]
	v_mfma_f32_16x16x32_bf16 v[14:17], v[144:147], v[210:213], v[14:17]
	v_mfma_f32_16x16x32_bf16 v[10:13], v[156:159], v[210:213], v[10:13]
	s_setprio 0
	s_setprio 1
	v_mfma_f32_16x16x32_bf16 v[54:57], v[160:163], v[176:179], 0
	v_mfma_f32_16x16x32_bf16 v[50:53], v[168:171], v[176:179], 0
	v_mfma_f32_16x16x32_bf16 v[38:41], v[160:163], v[184:187], 0
	v_mfma_f32_16x16x32_bf16 v[34:37], v[168:171], v[184:187], 0
	v_mfma_f32_16x16x32_bf16 v[22:25], v[160:163], v[198:201], 0
	v_mfma_f32_16x16x32_bf16 v[18:21], v[168:171], v[198:201], 0
	v_mfma_f32_16x16x32_bf16 v[6:9], v[160:163], v[206:209], 0
	v_mfma_f32_16x16x32_bf16 v[2:5], v[168:171], v[206:209], 0
	v_mfma_f32_16x16x32_bf16 v[54:57], v[164:167], v[180:183], v[54:57]
	v_mfma_f32_16x16x32_bf16 v[50:53], v[172:175], v[180:183], v[50:53]
	v_mfma_f32_16x16x32_bf16 v[38:41], v[164:167], v[194:197], v[38:41]
	v_mfma_f32_16x16x32_bf16 v[34:37], v[172:175], v[194:197], v[34:37]
	v_mfma_f32_16x16x32_bf16 v[22:25], v[164:167], v[202:205], v[22:25]
	v_mfma_f32_16x16x32_bf16 v[18:21], v[172:175], v[202:205], v[18:21]
	v_mfma_f32_16x16x32_bf16 v[6:9], v[164:167], v[210:213], v[6:9]
	v_mfma_f32_16x16x32_bf16 v[2:5], v[172:175], v[210:213], v[2:5]
	s_setprio 0
	s_barrier
	s_add_i32 s53, 0, 0x18000
	s_add_i32 s62, 0, 0x1c000
	v_add_u32_e32 v156, s53, v149
	v_add_u32_e32 v172, s62, v149
	ds_read_b128 v[140:143], v156
	ds_read_b128 v[144:147], v156 offset:1024
	ds_read_b128 v[152:155], v156 offset:2048
	ds_read_b128 v[156:159], v156 offset:3072
	ds_read_b128 v[160:163], v172
	ds_read_b128 v[164:167], v172 offset:1024
	ds_read_b128 v[168:171], v172 offset:2048
	ds_read_b128 v[172:175], v172 offset:3072
	s_add_u32 s60, s60, 0x40000
	s_addc_u32 s61, s61, 0
	s_mov_b32 m0, s27
	v_lshl_add_u64 v[220:221], s[60:61], 0, v[130:131]
	ds_read_b128 v[176:179], v151 offset:32768
	ds_read_b128 v[180:183], v151 offset:33792
	ds_read_b128 v[184:187], v151 offset:34816
	ds_read_b128 v[194:197], v151 offset:35840
	ds_read_b128 v[198:201], v151 offset:36864
	ds_read_b128 v[202:205], v151 offset:37888
	ds_read_b128 v[206:209], v151 offset:38912
	ds_read_b128 v[210:213], v151 offset:39936
	global_load_lds_dwordx4 v[220:221], off
	v_lshl_add_u64 v[220:221], s[60:61], 0, v[132:133]
	s_mov_b32 m0, s28
	s_nop 0
	global_load_lds_dwordx4 v[220:221], off
	s_waitcnt vmcnt(8)
	s_waitcnt lgkmcnt(0)
	s_barrier
	s_setprio 1
	s_waitcnt lgkmcnt(0)
	v_mfma_f32_16x16x32_bf16 v[126:129], v[140:143], v[176:179], v[126:129]
	v_mfma_f32_16x16x32_bf16 v[122:125], v[152:155], v[176:179], v[122:125]
	v_mfma_f32_16x16x32_bf16 v[118:121], v[140:143], v[184:187], v[118:121]
	v_mfma_f32_16x16x32_bf16 v[110:113], v[152:155], v[184:187], v[110:113]
	v_mfma_f32_16x16x32_bf16 v[94:97], v[140:143], v[198:201], v[94:97]
	v_mfma_f32_16x16x32_bf16 v[90:93], v[152:155], v[198:201], v[90:93]
	v_mfma_f32_16x16x32_bf16 v[78:81], v[140:143], v[206:209], v[78:81]
	v_mfma_f32_16x16x32_bf16 v[74:77], v[152:155], v[206:209], v[74:77]
	v_mfma_f32_16x16x32_bf16 v[126:129], v[144:147], v[180:183], v[126:129]
	v_mfma_f32_16x16x32_bf16 v[122:125], v[156:159], v[180:183], v[122:125]
	v_mfma_f32_16x16x32_bf16 v[118:121], v[144:147], v[194:197], v[118:121]
	v_mfma_f32_16x16x32_bf16 v[110:113], v[156:159], v[194:197], v[110:113]
	v_mfma_f32_16x16x32_bf16 v[94:97], v[144:147], v[202:205], v[94:97]
	v_mfma_f32_16x16x32_bf16 v[90:93], v[156:159], v[202:205], v[90:93]
	v_mfma_f32_16x16x32_bf16 v[78:81], v[144:147], v[210:213], v[78:81]
	v_mfma_f32_16x16x32_bf16 v[74:77], v[156:159], v[210:213], v[74:77]
	s_setprio 0
	s_setprio 1
	v_mfma_f32_16x16x32_bf16 v[114:117], v[160:163], v[176:179], v[114:117]
	v_mfma_f32_16x16x32_bf16 v[106:109], v[168:171], v[176:179], v[106:109]
	v_mfma_f32_16x16x32_bf16 v[102:105], v[160:163], v[184:187], v[102:105]
	v_mfma_f32_16x16x32_bf16 v[98:101], v[168:171], v[184:187], v[98:101]
	v_mfma_f32_16x16x32_bf16 v[86:89], v[160:163], v[198:201], v[86:89]
	v_mfma_f32_16x16x32_bf16 v[82:85], v[168:171], v[198:201], v[82:85]
	v_mfma_f32_16x16x32_bf16 v[70:73], v[160:163], v[206:209], v[70:73]
	v_mfma_f32_16x16x32_bf16 v[66:69], v[168:171], v[206:209], v[66:69]
	v_mfma_f32_16x16x32_bf16 v[114:117], v[164:167], v[180:183], v[114:117]
	v_mfma_f32_16x16x32_bf16 v[106:109], v[172:175], v[180:183], v[106:109]
	v_mfma_f32_16x16x32_bf16 v[102:105], v[164:167], v[194:197], v[102:105]
	v_mfma_f32_16x16x32_bf16 v[98:101], v[172:175], v[194:197], v[98:101]
	v_mfma_f32_16x16x32_bf16 v[86:89], v[164:167], v[202:205], v[86:89]
	v_mfma_f32_16x16x32_bf16 v[82:85], v[172:175], v[202:205], v[82:85]
	v_mfma_f32_16x16x32_bf16 v[70:73], v[164:167], v[210:213], v[70:73]
	v_mfma_f32_16x16x32_bf16 v[66:69], v[172:175], v[210:213], v[66:69]
	s_setprio 0
	s_barrier
; #define PG8_STAGE(bufoff, gbase, voff) do { _Pragma("unroll") for (int _i = 0; _i < 2; ++_i) \
;         __builtin_amdgcn_global_load_lds((const unsigned*)((const char*)(gbase) + (voff)[_i]), (PG8_LAS unsigned*)(lds + (bufoff) + ldsw + _i * 8192), 16, 0, 0); } while (0)
; #define PG8_LDA(dst, b, h) do { _Pragma("unroll") for (int m = 0; m < 4; ++m) _Pragma("unroll") for (int k = 0; k < 2; ++k) dst[m][k] = *(const PG8_LAS bf16x8*)(lds + PG8_SA(b, h) + aoff + m * 2048 + k * 1024); } while (0)
; #define PG8_MMA(ai, bj, At, Bt) do { __builtin_amdgcn_s_setprio(1); _Pragma("unroll") for (int m = 0; m < 4; ++m) _Pragma("unroll") for (int n = 0; n < 2; ++n) _Pragma("unroll") for (int k = 0; k < 2; ++k) \
;         acc[ai][bj][m][n] = __builtin_amdgcn_mfma_f32_16x16x32_bf16(Bt[n][k], At[m][k], acc[ai][bj][m][n], 0, 0, 0); __builtin_amdgcn_s_setprio(0); } while (0)
; #define PG8_WAIT_V(n) asm volatile("s_waitcnt vmcnt(" #n ")" ::: "memory")
; #define PG8_WAIT_L(n) asm volatile("s_waitcnt lgkmcnt(" #n ")" ::: "memory")
; #define PG8_BAR __builtin_amdgcn_s_barrier()
; #define PG8_SCHED __builtin_amdgcn_sched_barrier(0)
; template <class Epi, class Sched, bool ALIGN_EPI = false, bool SP2 = false>
; __device__ __forceinline__ void gemm_phase(PG8_LAS unsigned char* lds, const Gemm g, const Sched& S, const Epi& E) {
;     ...
;             PG8_LDA(At, 1, 1); PG8_STAGE(PG8_SB(1, 0), b3, voffB); PG8_STAGE(PG8_SB(1, 1), b3 + hstep, voffB); PG8_STAGE(PG8_SA(1, 0), a3, voffA);
;             PG8_WAIT_V(8); PG8_WAIT_L(0); PG8_BAR; PG8_MMA(1, 0, At, B0); PG8_MMA(1, 1, At, B1); PG8_BAR; PG8_SCHED;
	s_add_i32 s53, s53, s24
	v_lshl_add_u64 v[188:189], v[188:189], 0, s[8:9]
	s_mov_b32 m0, s53
	ds_read_b128 v[176:179], v151 offset:49152
	ds_read_b128 v[180:183], v151 offset:50176
	ds_read_b128 v[184:187], v151 offset:51200
	ds_read_b128 v[194:197], v151 offset:52224
	ds_read_b128 v[198:201], v151 offset:53248
	ds_read_b128 v[202:205], v151 offset:54272
	ds_read_b128 v[206:209], v151 offset:55296
	ds_read_b128 v[210:213], v151 offset:56320
	global_load_lds_dwordx4 v[188:189], off
	s_add_i32 m0, s53, 0x2000
	s_add_u32 s58, s58, 0x40080
	v_lshl_add_u64 v[188:189], v[214:215], 0, s[8:9]
	s_addc_u32 s59, s59, 0
	s_add_i32 s53, s62, s24
	global_load_lds_dwordx4 v[188:189], off
	v_lshl_add_u64 v[188:189], s[58:59], 0, v[0:1]
	s_mov_b32 m0, s53
	s_nop 0
	global_load_lds_dwordx4 v[188:189], off
	v_lshl_add_u64 v[188:189], s[58:59], 0, v[134:135]
	s_add_i32 m0, s53, 0x2000
	s_nop 0
	global_load_lds_dwordx4 v[188:189], off
	v_lshl_add_u64 v[188:189], v[216:217], 0, s[8:9]
	s_mov_b32 m0, s29
	s_nop 0
	global_load_lds_dwordx4 v[188:189], off
	v_lshl_add_u64 v[188:189], v[218:219], 0, s[8:9]
	s_mov_b32 m0, s55
	s_nop 0
	global_load_lds_dwordx4 v[188:189], off
	s_waitcnt vmcnt(8)
	s_waitcnt lgkmcnt(0)
	s_barrier
	s_setprio 1
	s_waitcnt lgkmcnt(0)
	v_mfma_f32_16x16x32_bf16 v[62:65], v[140:143], v[176:179], v[62:65]
	v_mfma_f32_16x16x32_bf16 v[58:61], v[152:155], v[176:179], v[58:61]
	v_mfma_f32_16x16x32_bf16 v[46:49], v[140:143], v[184:187], v[46:49]
	v_mfma_f32_16x16x32_bf16 v[42:45], v[152:155], v[184:187], v[42:45]
	v_mfma_f32_16x16x32_bf16 v[30:33], v[140:143], v[198:201], v[30:33]
	v_mfma_f32_16x16x32_bf16 v[26:29], v[152:155], v[198:201], v[26:29]
	v_mfma_f32_16x16x32_bf16 v[14:17], v[140:143], v[206:209], v[14:17]
	v_mfma_f32_16x16x32_bf16 v[10:13], v[152:155], v[206:209], v[10:13]
	v_mfma_f32_16x16x32_bf16 v[62:65], v[144:147], v[180:183], v[62:65]
	v_mfma_f32_16x16x32_bf16 v[58:61], v[156:159], v[180:183], v[58:61]
	v_mfma_f32_16x16x32_bf16 v[46:49], v[144:147], v[194:197], v[46:49]
	v_mfma_f32_16x16x32_bf16 v[42:45], v[156:159], v[194:197], v[42:45]
	v_mfma_f32_16x16x32_bf16 v[30:33], v[144:147], v[202:205], v[30:33]
	v_mfma_f32_16x16x32_bf16 v[26:29], v[156:159], v[202:205], v[26:29]
	v_mfma_f32_16x16x32_bf16 v[14:17], v[144:147], v[210:213], v[14:17]
	v_mfma_f32_16x16x32_bf16 v[10:13], v[156:159], v[210:213], v[10:13]
	s_setprio 0
	s_setprio 1
	v_mfma_f32_16x16x32_bf16 v[54:57], v[160:163], v[176:179], v[54:57]
	v_mfma_f32_16x16x32_bf16 v[50:53], v[168:171], v[176:179], v[50:53]
	v_mfma_f32_16x16x32_bf16 v[38:41], v[160:163], v[184:187], v[38:41]
	v_mfma_f32_16x16x32_bf16 v[34:37], v[168:171], v[184:187], v[34:37]
	v_mfma_f32_16x16x32_bf16 v[22:25], v[160:163], v[198:201], v[22:25]
	v_mfma_f32_16x16x32_bf16 v[18:21], v[168:171], v[198:201], v[18:21]
	v_mfma_f32_16x16x32_bf16 v[6:9], v[160:163], v[206:209], v[6:9]
	v_mfma_f32_16x16x32_bf16 v[2:5], v[168:171], v[206:209], v[2:5]
	v_mfma_f32_16x16x32_bf16 v[54:57], v[164:167], v[180:183], v[54:57]
	v_mfma_f32_16x16x32_bf16 v[50:53], v[172:175], v[180:183], v[50:53]
	v_mfma_f32_16x16x32_bf16 v[38:41], v[164:167], v[194:197], v[38:41]
	v_mfma_f32_16x16x32_bf16 v[34:37], v[172:175], v[194:197], v[34:37]
	v_mfma_f32_16x16x32_bf16 v[22:25], v[164:167], v[202:205], v[22:25]
	v_mfma_f32_16x16x32_bf16 v[18:21], v[172:175], v[202:205], v[18:21]
	v_mfma_f32_16x16x32_bf16 v[6:9], v[164:167], v[210:213], v[6:9]
	v_mfma_f32_16x16x32_bf16 v[2:5], v[172:175], v[210:213], v[2:5]
	s_setprio 0
	s_barrier
	s_add_i32 s52, s52, 2
	s_add_u32 s18, s18, 0x100
	s_addc_u32 s19, s19, 0
	s_add_u32 s43, s43, 0x100
	s_addc_u32 s45, s45, 0
	s_cmp_gt_u32 s52, 13

; template <class Epi, class Sched, bool ALIGN_EPI = false, bool SP2 = false>
; __device__ __forceinline__ void gemm_phase(PG8_LAS unsigned char* lds, const Gemm g, const Sched& S, const Epi& E) {
;     ...
;         const bool has_next = S.next(ui + 1, nxt);
;         const char* nA = has_next ? (const char*)g.A + (size_t)nxt.pm * tstep : cA; const char* nB = has_next ? (const char*)g.Bt + (size_t)nxt.pn * tstep : cB;
;         for (int t = 0; t < nt; t += 2) {
.LBB0_556:
	s_ashr_i32 s43, s42, 31
	s_lshl_b64 s[30:31], s[42:43], 19
	s_add_u32 s46, s96, s30
	s_addc_u32 s47, s97, s31
	s_and_b64 s[30:31], s[44:45], exec
	s_cselect_b32 s30, s47, s19
	s_cselect_b32 s31, s46, s18
	s_ashr_i32 s41, s40, 31
	s_lshl_b64 s[34:35], s[40:41], 19
	s_add_u32 s48, s24, s34
	s_addc_u32 s49, s25, s35
	s_and_b64 s[34:35], s[44:45], exec
	s_cselect_b32 s34, s49, s57
	s_cselect_b32 s35, s48, s56
	s_add_u32 s18, s18, 0x40080
	s_addc_u32 s19, s19, 0
	s_add_u32 s41, s56, 0x100

; template <class Epi, class Sched, bool ALIGN_EPI = false, bool SP2 = false>
; __device__ __forceinline__ void gemm_phase(PG8_LAS unsigned char* lds, const Gemm g, const Sched& S, const Epi& E) {
;     ...
;         for (int t = 0; t < nt; t += 2) {
;             const bool last = (t == nt - 2);
;             const char* a1 = cA + (size_t)(t + 1) * kstep;
;             const char* a2 = last ? nA : cA + (size_t)(t + 2) * kstep; const char* b2 = last ? nB : cB + (size_t)(t + 2) * kstep;
	s_addc_u32 s43, s57, 0
	s_mov_b32 s52, -2


; #define PG8_STAGE(bufoff, gbase, voff) do { _Pragma("unroll") for (int _i = 0; _i < 2; ++_i) \
;         __builtin_amdgcn_global_load_lds((const unsigned*)((const char*)(gbase) + (voff)[_i]), (PG8_LAS unsigned*)(lds + (bufoff) + ldsw + _i * 8192), 16, 0, 0); } while (0)
; #define PG8_LDA(dst, b, h) do { _Pragma("unroll") for (int m = 0; m < 4; ++m) _Pragma("unroll") for (int k = 0; k < 2; ++k) dst[m][k] = *(const PG8_LAS bf16x8*)(lds + PG8_SA(b, h) + aoff + m * 2048 + k * 1024); } while (0)
; #define PG8_LDB(dst, b, h) do { _Pragma("unroll") for (int n = 0; n < 2; ++n) _Pragma("unroll") for (int k = 0; k < 2; ++k) dst[n][k] = *(const PG8_LAS bf16x8*)(lds + PG8_SB(b, h) + boff + n * 2048 + k * 1024); } while (0)
; #define PG8_MMA(ai, bj, At, Bt) do { __builtin_amdgcn_s_setprio(1); _Pragma("unroll") for (int m = 0; m < 4; ++m) _Pragma("unroll") for (int n = 0; n < 2; ++n) _Pragma("unroll") for (int k = 0; k < 2; ++k) \
;         acc[ai][bj][m][n] = __builtin_amdgcn_mfma_f32_16x16x32_bf16(Bt[n][k], At[m][k], acc[ai][bj][m][n], 0, 0, 0); __builtin_amdgcn_s_setprio(0); } while (0)
; #define PG8_WAIT_V(n) asm volatile("s_waitcnt vmcnt(" #n ")" ::: "memory")
; #define PG8_WAIT_L(n) asm volatile("s_waitcnt lgkmcnt(" #n ")" ::: "memory")
; #define PG8_BAR __builtin_amdgcn_s_barrier()
; #define PG8_SCHED __builtin_amdgcn_sched_barrier(0)
; template <class Epi, class Sched, bool ALIGN_EPI = false, bool SP2 = false>
; __device__ __forceinline__ void gemm_phase(PG8_LAS unsigned char* lds, const Gemm g, const Sched& S, const Epi& E) {
;     ...
;             const char* a2 = last ? nA : cA + (size_t)(t + 2) * kstep; const char* b2 = last ? nB : cB + (size_t)(t + 2) * kstep;
;             const char* a3 = a2 + kstep; const char* b3 = b2 + kstep;
;             if (last && has_next) S.a_ready(nxt);
;             if constexpr (SP2) {
;             PG8_LDB(B0, 0, 0); PG8_LDB(B1, 0, 1); PG8_SCHED; PG8_LDA(At, 0, 0); PG8_STAGE(PG8_SA(1, 1), a1 + hstep, voffA);
;             PG8_WAIT_V(8); PG8_WAIT_L(0); PG8_BAR; PG8_MMA(0, 0, At, B0); PG8_MMA(0, 1, At, B1); PG8_BAR; PG8_SCHED;
;             PG8_LDA(At, 0, 1); PG8_STAGE(PG8_SB(0, 0), b2, voffB); PG8_STAGE(PG8_SB(0, 1), b2 + hstep, voffB); PG8_STAGE(PG8_SA(0, 0), a2, voffA);
;             PG8_WAIT_V(8); PG8_WAIT_L(0); PG8_BAR; PG8_MMA(1, 0, At, B0); PG8_MMA(1, 1, At, B1); PG8_BAR; PG8_SCHED;
	s_add_u32 s53, s18, 0xfffc0080
	s_addc_u32 s56, s19, -1
	s_add_i32 s60, 0, 0x10000
	s_cmp_eq_u32 s52, 12
	s_cselect_b32 s59, s30, s56
	s_cselect_b32 s58, s31, s53
	s_cselect_b32 s57, s34, s43
	s_cselect_b32 s56, s35, s41
	s_add_i32 s53, 0, 0x14000
	v_add_u32_e32 v152, s60, v161
	v_add_u32_e32 v172, s53, v161
	ds_read_b128 v[140:143], v152
	ds_read_b128 v[144:147], v152 offset:1024
	ds_read_b128 v[148:151], v152 offset:2048
	ds_read_b128 v[152:155], v152 offset:3072
	ds_read_b128 v[156:159], v172
	ds_read_b128 v[164:167], v172 offset:1024
	ds_read_b128 v[168:171], v172 offset:2048
	ds_read_b128 v[172:175], v172 offset:3072
	v_lshl_add_u64 v[188:189], s[18:19], 0, v[136:137]
	s_add_i32 m0, s26, 0xc000
	ds_read_b128 v[176:179], v163
	ds_read_b128 v[180:183], v163 offset:1024
	ds_read_b128 v[184:187], v163 offset:2048
	ds_read_b128 v[194:197], v163 offset:3072
	ds_read_b128 v[198:201], v163 offset:4096
	ds_read_b128 v[202:205], v163 offset:5120
	ds_read_b128 v[206:209], v163 offset:6144
	ds_read_b128 v[210:213], v163 offset:7168
	global_load_lds_dwordx4 v[188:189], off
	v_lshl_add_u64 v[188:189], s[18:19], 0, v[138:139]
	s_add_i32 m0, s26, 0xe000
	s_nop 0
	global_load_lds_dwordx4 v[188:189], off
	s_waitcnt vmcnt(8)
	s_waitcnt lgkmcnt(0)
	s_barrier
	s_setprio 1
	s_waitcnt lgkmcnt(0)
	v_mfma_f32_16x16x32_bf16 v[126:129], v[140:143], v[176:179], 0
	v_mfma_f32_16x16x32_bf16 v[122:125], v[148:151], v[176:179], 0
	v_mfma_f32_16x16x32_bf16 v[118:121], v[140:143], v[184:187], 0
	v_mfma_f32_16x16x32_bf16 v[106:109], v[148:151], v[184:187], 0
	v_mfma_f32_16x16x32_bf16 v[94:97], v[140:143], v[198:201], 0
	v_mfma_f32_16x16x32_bf16 v[90:93], v[148:151], v[198:201], 0
	v_mfma_f32_16x16x32_bf16 v[78:81], v[140:143], v[206:209], 0
	v_mfma_f32_16x16x32_bf16 v[74:77], v[148:151], v[206:209], 0
	v_mfma_f32_16x16x32_bf16 v[126:129], v[144:147], v[180:183], v[126:129]
	v_mfma_f32_16x16x32_bf16 v[122:125], v[152:155], v[180:183], v[122:125]
	v_mfma_f32_16x16x32_bf16 v[118:121], v[144:147], v[194:197], v[118:121]
	v_mfma_f32_16x16x32_bf16 v[106:109], v[152:155], v[194:197], v[106:109]
	v_mfma_f32_16x16x32_bf16 v[94:97], v[144:147], v[202:205], v[94:97]
	v_mfma_f32_16x16x32_bf16 v[90:93], v[152:155], v[202:205], v[90:93]
	v_mfma_f32_16x16x32_bf16 v[78:81], v[144:147], v[210:213], v[78:81]
	v_mfma_f32_16x16x32_bf16 v[74:77], v[152:155], v[210:213], v[74:77]
	s_setprio 0
	s_setprio 1
	v_mfma_f32_16x16x32_bf16 v[114:117], v[156:159], v[176:179], 0
	v_mfma_f32_16x16x32_bf16 v[110:113], v[168:171], v[176:179], 0
	v_mfma_f32_16x16x32_bf16 v[102:105], v[156:159], v[184:187], 0
	v_mfma_f32_16x16x32_bf16 v[98:101], v[168:171], v[184:187], 0
	v_mfma_f32_16x16x32_bf16 v[86:89], v[156:159], v[198:201], 0
	v_mfma_f32_16x16x32_bf16 v[82:85], v[168:171], v[198:201], 0
	v_mfma_f32_16x16x32_bf16 v[70:73], v[156:159], v[206:209], 0
	v_mfma_f32_16x16x32_bf16 v[66:69], v[168:171], v[206:209], 0
	v_mfma_f32_16x16x32_bf16 v[114:117], v[164:167], v[180:183], v[114:117]
	v_mfma_f32_16x16x32_bf16 v[110:113], v[172:175], v[180:183], v[110:113]
	v_mfma_f32_16x16x32_bf16 v[102:105], v[164:167], v[194:197], v[102:105]
	v_mfma_f32_16x16x32_bf16 v[98:101], v[172:175], v[194:197], v[98:101]
	v_mfma_f32_16x16x32_bf16 v[86:89], v[164:167], v[202:205], v[86:89]
	v_mfma_f32_16x16x32_bf16 v[82:85], v[172:175], v[202:205], v[82:85]
	v_mfma_f32_16x16x32_bf16 v[70:73], v[164:167], v[210:213], v[70:73]
	v_mfma_f32_16x16x32_bf16 v[66:69], v[172:175], v[210:213], v[66:69]
	s_setprio 0
	s_barrier
	s_add_i32 s60, s60, s23
	v_lshl_add_u64 v[188:189], s[56:57], 0, v[0:1]
	s_mov_b32 m0, s60
	ds_read_b128 v[176:179], v163 offset:16384
	ds_read_b128 v[180:183], v163 offset:17408
	ds_read_b128 v[184:187], v163 offset:18432
	ds_read_b128 v[194:197], v163 offset:19456
	ds_read_b128 v[198:201], v163 offset:20480
	ds_read_b128 v[202:205], v163 offset:21504
	ds_read_b128 v[206:209], v163 offset:22528
	ds_read_b128 v[210:213], v163 offset:23552
	global_load_lds_dwordx4 v[188:189], off
	s_add_i32 m0, s60, 0x2000
	s_add_u32 s60, s56, 0x40000
	v_lshl_add_u64 v[214:215], s[56:57], 0, v[134:135]
	s_addc_u32 s61, s57, 0
	s_add_i32 s53, s53, s23
	global_load_lds_dwordx4 v[214:215], off
	v_lshl_add_u64 v[216:217], s[60:61], 0, v[0:1]
	s_mov_b32 m0, s53
	v_lshl_add_u64 v[218:219], s[58:59], 0, v[132:133]
	global_load_lds_dwordx4 v[216:217], off
	v_lshl_add_u64 v[216:217], s[60:61], 0, v[134:135]
	s_add_i32 m0, s53, 0x2000
	s_nop 0
	global_load_lds_dwordx4 v[216:217], off
	v_lshl_add_u64 v[216:217], s[58:59], 0, v[130:131]
	s_mov_b32 m0, s26
	s_nop 0
	global_load_lds_dwordx4 v[216:217], off
	s_mov_b32 m0, s27
	s_nop 0
	global_load_lds_dwordx4 v[218:219], off
	s_waitcnt vmcnt(8)
	s_waitcnt lgkmcnt(0)
	s_barrier
; #define PG8_STAGE(bufoff, gbase, voff) do { _Pragma("unroll") for (int _i = 0; _i < 2; ++_i) \
;         __builtin_amdgcn_global_load_lds((const unsigned*)((const char*)(gbase) + (voff)[_i]), (PG8_LAS unsigned*)(lds + (bufoff) + ldsw + _i * 8192), 16, 0, 0); } while (0)
; #define PG8_LDA(dst, b, h) do { _Pragma("unroll") for (int m = 0; m < 4; ++m) _Pragma("unroll") for (int k = 0; k < 2; ++k) dst[m][k] = *(const PG8_LAS bf16x8*)(lds + PG8_SA(b, h) + aoff + m * 2048 + k * 1024); } while (0)
; #define PG8_LDB(dst, b, h) do { _Pragma("unroll") for (int n = 0; n < 2; ++n) _Pragma("unroll") for (int k = 0; k < 2; ++k) dst[n][k] = *(const PG8_LAS bf16x8*)(lds + PG8_SB(b, h) + boff + n * 2048 + k * 1024); } while (0)
; #define PG8_MMA(ai, bj, At, Bt) do { __builtin_amdgcn_s_setprio(1); _Pragma("unroll") for (int m = 0; m < 4; ++m) _Pragma("unroll") for (int n = 0; n < 2; ++n) _Pragma("unroll") for (int k = 0; k < 2; ++k) \
;         acc[ai][bj][m][n] = __builtin_amdgcn_mfma_f32_16x16x32_bf16(Bt[n][k], At[m][k], acc[ai][bj][m][n], 0, 0, 0); __builtin_amdgcn_s_setprio(0); } while (0)
; #define PG8_WAIT_V(n) asm volatile("s_waitcnt vmcnt(" #n ")" ::: "memory")
; #define PG8_WAIT_L(n) asm volatile("s_waitcnt lgkmcnt(" #n ")" ::: "memory")
; #define PG8_BAR __builtin_amdgcn_s_barrier()
; #define PG8_SCHED __builtin_amdgcn_sched_barrier(0)
; template <class Epi, class Sched, bool ALIGN_EPI = false, bool SP2 = false>
; __device__ __forceinline__ void gemm_phase(PG8_LAS unsigned char* lds, const Gemm g, const Sched& S, const Epi& E) {
;     ...
;             PG8_WAIT_V(8); PG8_WAIT_L(0); PG8_BAR; PG8_MMA(1, 0, At, B0); PG8_MMA(1, 1, At, B1); PG8_BAR; PG8_SCHED;
;             PG8_LDB(B0, 1, 0); PG8_LDB(B1, 1, 1); PG8_SCHED; PG8_LDA(At, 1, 0); PG8_STAGE(PG8_SA(0, 1), a2 + hstep, voffA);
;             PG8_WAIT_V(8); PG8_WAIT_L(0); PG8_BAR; PG8_MMA(0, 0, At, B0); PG8_MMA(0, 1, At, B1); PG8_BAR; PG8_SCHED;
	s_setprio 1
	s_waitcnt lgkmcnt(0)
	v_mfma_f32_16x16x32_bf16 v[62:65], v[140:143], v[176:179], 0
	v_mfma_f32_16x16x32_bf16 v[58:61], v[148:151], v[176:179], 0
	v_mfma_f32_16x16x32_bf16 v[46:49], v[140:143], v[184:187], 0
	v_mfma_f32_16x16x32_bf16 v[42:45], v[148:151], v[184:187], 0
	v_mfma_f32_16x16x32_bf16 v[30:33], v[140:143], v[198:201], 0
	v_mfma_f32_16x16x32_bf16 v[26:29], v[148:151], v[198:201], 0
	v_mfma_f32_16x16x32_bf16 v[14:17], v[140:143], v[206:209], 0
	v_mfma_f32_16x16x32_bf16 v[10:13], v[148:151], v[206:209], 0
	v_mfma_f32_16x16x32_bf16 v[62:65], v[144:147], v[180:183], v[62:65]
	v_mfma_f32_16x16x32_bf16 v[58:61], v[152:155], v[180:183], v[58:61]
	v_mfma_f32_16x16x32_bf16 v[46:49], v[144:147], v[194:197], v[46:49]
	v_mfma_f32_16x16x32_bf16 v[42:45], v[152:155], v[194:197], v[42:45]
	v_mfma_f32_16x16x32_bf16 v[30:33], v[144:147], v[202:205], v[30:33]
	v_mfma_f32_16x16x32_bf16 v[26:29], v[152:155], v[202:205], v[26:29]
	v_mfma_f32_16x16x32_bf16 v[14:17], v[144:147], v[210:213], v[14:17]
	v_mfma_f32_16x16x32_bf16 v[10:13], v[152:155], v[210:213], v[10:13]
	s_setprio 0
	s_setprio 1
	v_mfma_f32_16x16x32_bf16 v[54:57], v[156:159], v[176:179], 0
	v_mfma_f32_16x16x32_bf16 v[50:53], v[168:171], v[176:179], 0
	v_mfma_f32_16x16x32_bf16 v[38:41], v[156:159], v[184:187], 0
	v_mfma_f32_16x16x32_bf16 v[34:37], v[168:171], v[184:187], 0
	v_mfma_f32_16x16x32_bf16 v[22:25], v[156:159], v[198:201], 0
	v_mfma_f32_16x16x32_bf16 v[18:21], v[168:171], v[198:201], 0
	v_mfma_f32_16x16x32_bf16 v[6:9], v[156:159], v[206:209], 0
	v_mfma_f32_16x16x32_bf16 v[2:5], v[168:171], v[206:209], 0
	v_mfma_f32_16x16x32_bf16 v[54:57], v[164:167], v[180:183], v[54:57]
	v_mfma_f32_16x16x32_bf16 v[50:53], v[172:175], v[180:183], v[50:53]
	v_mfma_f32_16x16x32_bf16 v[38:41], v[164:167], v[194:197], v[38:41]
	v_mfma_f32_16x16x32_bf16 v[34:37], v[172:175], v[194:197], v[34:37]
	v_mfma_f32_16x16x32_bf16 v[22:25], v[164:167], v[202:205], v[22:25]
	v_mfma_f32_16x16x32_bf16 v[18:21], v[172:175], v[202:205], v[18:21]
	v_mfma_f32_16x16x32_bf16 v[6:9], v[164:167], v[210:213], v[6:9]
	v_mfma_f32_16x16x32_bf16 v[2:5], v[172:175], v[210:213], v[2:5]
	s_setprio 0
	s_barrier
	s_add_i32 s53, 0, 0x18000
	s_add_i32 s60, 0, 0x1c000
	v_add_u32_e32 v152, s53, v161
	v_add_u32_e32 v172, s60, v161
	ds_read_b128 v[140:143], v152
	ds_read_b128 v[144:147], v152 offset:1024
	ds_read_b128 v[148:151], v152 offset:2048
	ds_read_b128 v[152:155], v152 offset:3072
	ds_read_b128 v[156:159], v172
	ds_read_b128 v[164:167], v172 offset:1024
	ds_read_b128 v[168:171], v172 offset:2048
	ds_read_b128 v[172:175], v172 offset:3072
	s_add_u32 s58, s58, 0x40000
	s_addc_u32 s59, s59, 0
	s_mov_b32 m0, s28
	v_lshl_add_u64 v[220:221], s[58:59], 0, v[130:131]
	ds_read_b128 v[176:179], v163 offset:32768
	ds_read_b128 v[180:183], v163 offset:33792
	ds_read_b128 v[184:187], v163 offset:34816
	ds_read_b128 v[194:197], v163 offset:35840
	ds_read_b128 v[198:201], v163 offset:36864
	ds_read_b128 v[202:205], v163 offset:37888
	ds_read_b128 v[206:209], v163 offset:38912
	ds_read_b128 v[210:213], v163 offset:39936
	global_load_lds_dwordx4 v[220:221], off
	v_lshl_add_u64 v[220:221], s[58:59], 0, v[132:133]
	s_mov_b32 m0, s29
	s_nop 0
	global_load_lds_dwordx4 v[220:221], off
	s_waitcnt vmcnt(8)
	s_waitcnt lgkmcnt(0)
	s_barrier
	s_setprio 1
	s_waitcnt lgkmcnt(0)
	v_mfma_f32_16x16x32_bf16 v[126:129], v[140:143], v[176:179], v[126:129]
	v_mfma_f32_16x16x32_bf16 v[122:125], v[148:151], v[176:179], v[122:125]
	v_mfma_f32_16x16x32_bf16 v[118:121], v[140:143], v[184:187], v[118:121]
	v_mfma_f32_16x16x32_bf16 v[106:109], v[148:151], v[184:187], v[106:109]
	v_mfma_f32_16x16x32_bf16 v[94:97], v[140:143], v[198:201], v[94:97]
	v_mfma_f32_16x16x32_bf16 v[90:93], v[148:151], v[198:201], v[90:93]
	v_mfma_f32_16x16x32_bf16 v[78:81], v[140:143], v[206:209], v[78:81]
	v_mfma_f32_16x16x32_bf16 v[74:77], v[148:151], v[206:209], v[74:77]
	v_mfma_f32_16x16x32_bf16 v[126:129], v[144:147], v[180:183], v[126:129]
	v_mfma_f32_16x16x32_bf16 v[122:125], v[152:155], v[180:183], v[122:125]
	v_mfma_f32_16x16x32_bf16 v[118:121], v[144:147], v[194:197], v[118:121]
	v_mfma_f32_16x16x32_bf16 v[106:109], v[152:155], v[194:197], v[106:109]
	v_mfma_f32_16x16x32_bf16 v[94:97], v[144:147], v[202:205], v[94:97]
	v_mfma_f32_16x16x32_bf16 v[90:93], v[152:155], v[202:205], v[90:93]
	v_mfma_f32_16x16x32_bf16 v[78:81], v[144:147], v[210:213], v[78:81]
	v_mfma_f32_16x16x32_bf16 v[74:77], v[152:155], v[210:213], v[74:77]
	s_setprio 0
	s_setprio 1
	v_mfma_f32_16x16x32_bf16 v[114:117], v[156:159], v[176:179], v[114:117]
	v_mfma_f32_16x16x32_bf16 v[110:113], v[168:171], v[176:179], v[110:113]
	v_mfma_f32_16x16x32_bf16 v[102:105], v[156:159], v[184:187], v[102:105]
	v_mfma_f32_16x16x32_bf16 v[98:101], v[168:171], v[184:187], v[98:101]
	v_mfma_f32_16x16x32_bf16 v[86:89], v[156:159], v[198:201], v[86:89]
	v_mfma_f32_16x16x32_bf16 v[82:85], v[168:171], v[198:201], v[82:85]
	v_mfma_f32_16x16x32_bf16 v[70:73], v[156:159], v[206:209], v[70:73]
	v_mfma_f32_16x16x32_bf16 v[66:69], v[168:171], v[206:209], v[66:69]
	v_mfma_f32_16x16x32_bf16 v[114:117], v[164:167], v[180:183], v[114:117]
	v_mfma_f32_16x16x32_bf16 v[110:113], v[172:175], v[180:183], v[110:113]
	v_mfma_f32_16x16x32_bf16 v[102:105], v[164:167], v[194:197], v[102:105]
	v_mfma_f32_16x16x32_bf16 v[98:101], v[172:175], v[194:197], v[98:101]
	v_mfma_f32_16x16x32_bf16 v[86:89], v[164:167], v[202:205], v[86:89]
	v_mfma_f32_16x16x32_bf16 v[82:85], v[172:175], v[202:205], v[82:85]
	v_mfma_f32_16x16x32_bf16 v[70:73], v[164:167], v[210:213], v[70:73]
	v_mfma_f32_16x16x32_bf16 v[66:69], v[172:175], v[210:213], v[66:69]
	s_setprio 0
	s_barrier
; #define PG8_STAGE(bufoff, gbase, voff) do { _Pragma("unroll") for (int _i = 0; _i < 2; ++_i) \
;         __builtin_amdgcn_global_load_lds((const unsigned*)((const char*)(gbase) + (voff)[_i]), (PG8_LAS unsigned*)(lds + (bufoff) + ldsw + _i * 8192), 16, 0, 0); } while (0)
; #define PG8_LDA(dst, b, h) do { _Pragma("unroll") for (int m = 0; m < 4; ++m) _Pragma("unroll") for (int k = 0; k < 2; ++k) dst[m][k] = *(const PG8_LAS bf16x8*)(lds + PG8_SA(b, h) + aoff + m * 2048 + k * 1024); } while (0)
; #define PG8_MMA(ai, bj, At, Bt) do { __builtin_amdgcn_s_setprio(1); _Pragma("unroll") for (int m = 0; m < 4; ++m) _Pragma("unroll") for (int n = 0; n < 2; ++n) _Pragma("unroll") for (int k = 0; k < 2; ++k) \
;         acc[ai][bj][m][n] = __builtin_amdgcn_mfma_f32_16x16x32_bf16(Bt[n][k], At[m][k], acc[ai][bj][m][n], 0, 0, 0); __builtin_amdgcn_s_setprio(0); } while (0)
; #define PG8_WAIT_V(n) asm volatile("s_waitcnt vmcnt(" #n ")" ::: "memory")
; #define PG8_WAIT_L(n) asm volatile("s_waitcnt lgkmcnt(" #n ")" ::: "memory")
; #define PG8_BAR __builtin_amdgcn_s_barrier()
; #define PG8_SCHED __builtin_amdgcn_sched_barrier(0)
; template <class Epi, class Sched, bool ALIGN_EPI = false, bool SP2 = false>
; __device__ __forceinline__ void gemm_phase(PG8_LAS unsigned char* lds, const Gemm g, const Sched& S, const Epi& E) {
;     ...
;             PG8_LDA(At, 1, 1); PG8_STAGE(PG8_SB(1, 0), b3, voffB); PG8_STAGE(PG8_SB(1, 1), b3 + hstep, voffB); PG8_STAGE(PG8_SA(1, 0), a3, voffA);
;             PG8_WAIT_V(8); PG8_WAIT_L(0); PG8_BAR; PG8_MMA(1, 0, At, B0); PG8_MMA(1, 1, At, B1); PG8_BAR; PG8_SCHED;
	s_add_i32 s53, s53, s23
	v_lshl_add_u64 v[188:189], v[188:189], 0, s[8:9]
	s_mov_b32 m0, s53
	ds_read_b128 v[176:179], v163 offset:49152
	ds_read_b128 v[180:183], v163 offset:50176
	ds_read_b128 v[184:187], v163 offset:51200
	ds_read_b128 v[194:197], v163 offset:52224
	ds_read_b128 v[198:201], v163 offset:53248
	ds_read_b128 v[202:205], v163 offset:54272
	ds_read_b128 v[206:209], v163 offset:55296
	ds_read_b128 v[210:213], v163 offset:56320
	global_load_lds_dwordx4 v[188:189], off
	s_add_i32 m0, s53, 0x2000
	s_add_u32 s56, s56, 0x40080
	v_lshl_add_u64 v[188:189], v[214:215], 0, s[8:9]
	s_addc_u32 s57, s57, 0
	s_add_i32 s53, s60, s23
	global_load_lds_dwordx4 v[188:189], off
	v_lshl_add_u64 v[188:189], s[56:57], 0, v[0:1]
	s_mov_b32 m0, s53
	s_nop 0
	global_load_lds_dwordx4 v[188:189], off
	v_lshl_add_u64 v[188:189], s[56:57], 0, v[134:135]
	s_add_i32 m0, s53, 0x2000
	s_nop 0
	global_load_lds_dwordx4 v[188:189], off
	v_lshl_add_u64 v[188:189], v[216:217], 0, s[8:9]
	s_mov_b32 m0, s22
	s_nop 0
	global_load_lds_dwordx4 v[188:189], off
	v_lshl_add_u64 v[188:189], v[218:219], 0, s[8:9]
	s_mov_b32 m0, s51
	s_nop 0
	global_load_lds_dwordx4 v[188:189], off
	s_waitcnt vmcnt(8)
	s_waitcnt lgkmcnt(0)
	s_barrier
	s_setprio 1
	s_waitcnt lgkmcnt(0)
	v_mfma_f32_16x16x32_bf16 v[62:65], v[140:143], v[176:179], v[62:65]
	v_mfma_f32_16x16x32_bf16 v[58:61], v[148:151], v[176:179], v[58:61]
	v_mfma_f32_16x16x32_bf16 v[46:49], v[140:143], v[184:187], v[46:49]
	v_mfma_f32_16x16x32_bf16 v[42:45], v[148:151], v[184:187], v[42:45]
	v_mfma_f32_16x16x32_bf16 v[30:33], v[140:143], v[198:201], v[30:33]
	v_mfma_f32_16x16x32_bf16 v[26:29], v[148:151], v[198:201], v[26:29]
	v_mfma_f32_16x16x32_bf16 v[14:17], v[140:143], v[206:209], v[14:17]
	v_mfma_f32_16x16x32_bf16 v[10:13], v[148:151], v[206:209], v[10:13]
	v_mfma_f32_16x16x32_bf16 v[62:65], v[144:147], v[180:183], v[62:65]
	v_mfma_f32_16x16x32_bf16 v[58:61], v[152:155], v[180:183], v[58:61]
	v_mfma_f32_16x16x32_bf16 v[46:49], v[144:147], v[194:197], v[46:49]
	v_mfma_f32_16x16x32_bf16 v[42:45], v[152:155], v[194:197], v[42:45]
	v_mfma_f32_16x16x32_bf16 v[30:33], v[144:147], v[202:205], v[30:33]
	v_mfma_f32_16x16x32_bf16 v[26:29], v[152:155], v[202:205], v[26:29]
	v_mfma_f32_16x16x32_bf16 v[14:17], v[144:147], v[210:213], v[14:17]
	v_mfma_f32_16x16x32_bf16 v[10:13], v[152:155], v[210:213], v[10:13]
	s_setprio 0
	s_setprio 1
	v_mfma_f32_16x16x32_bf16 v[54:57], v[156:159], v[176:179], v[54:57]
	v_mfma_f32_16x16x32_bf16 v[50:53], v[168:171], v[176:179], v[50:53]
	v_mfma_f32_16x16x32_bf16 v[38:41], v[156:159], v[184:187], v[38:41]
	v_mfma_f32_16x16x32_bf16 v[34:37], v[168:171], v[184:187], v[34:37]
	v_mfma_f32_16x16x32_bf16 v[22:25], v[156:159], v[198:201], v[22:25]
	v_mfma_f32_16x16x32_bf16 v[18:21], v[168:171], v[198:201], v[18:21]
	v_mfma_f32_16x16x32_bf16 v[6:9], v[156:159], v[206:209], v[6:9]
	v_mfma_f32_16x16x32_bf16 v[2:5], v[168:171], v[206:209], v[2:5]
	v_mfma_f32_16x16x32_bf16 v[54:57], v[164:167], v[180:183], v[54:57]
	v_mfma_f32_16x16x32_bf16 v[50:53], v[172:175], v[180:183], v[50:53]
	v_mfma_f32_16x16x32_bf16 v[38:41], v[164:167], v[194:197], v[38:41]
	v_mfma_f32_16x16x32_bf16 v[34:37], v[172:175], v[194:197], v[34:37]
	v_mfma_f32_16x16x32_bf16 v[22:25], v[164:167], v[202:205], v[22:25]
	v_mfma_f32_16x16x32_bf16 v[18:21], v[172:175], v[202:205], v[18:21]
	v_mfma_f32_16x16x32_bf16 v[6:9], v[164:167], v[210:213], v[6:9]
	v_mfma_f32_16x16x32_bf16 v[2:5], v[172:175], v[210:213], v[2:5]
	s_setprio 0
	s_barrier
	s_add_i32 s52, s52, 2
	s_add_u32 s18, s18, 0x100
	s_addc_u32 s19, s19, 0
	s_add_u32 s41, s41, 0x100
	s_addc_u32 s43, s43, 0
	s_cmp_gt_u32 s52, 13
